# workspace re-laid out as one private 41.5 MiB slab per blockIdx%8 group (per-array base += group*delta), so no cross-XCD overlay conflicts remain; all in-layer seams XCC-local
# speedup vs baseline: 1.0089x; 1.0089x over previous
; #define LAS __attribute__((address_space(3)))
; __global__ void __launch_bounds__(512) fwd_megakernel(KArgs a) {
;     ...
;     const int wave = __builtin_amdgcn_readfirstlane(threadIdx.x >> 6);
;     const int G = gridDim.x, bx = blockIdx.x;
;     volatile LAS unsigned* MISC = (volatile LAS unsigned*)(lds + 131072);
;     if (threadIdx.x < 16) MISC[threadIdx.x] = 0u;
;     __syncthreads();
;     XcdBarrier xbar = xcd_barrier_post((unsigned*)(a.ws + WS_CTL), MISC + 8);
_Z14fwd_megakernel5KArgs:
	s_load_dwordx2 s[68:69], s[0:1], 0xb0
	s_load_dwordx4 s[4:7], s[0:1], 0xa0
	s_load_dword s71, s[0:1], 0xc8
	s_load_dwordx2 s[84:85], s[0:1], 0xc0
	v_and_b32_e32 v202, 0x3ff, v0
	v_cmp_gt_u32_e32 vcc, 16, v202
	s_waitcnt lgkmcnt(0)
	v_writelane_b32 v252, s4, 0
	s_nop 1
	v_writelane_b32 v252, s5, 1
	v_writelane_b32 v252, s6, 2
	v_writelane_b32 v252, s7, 3
	s_load_dwordx8 s[4:11], s[0:1], 0x80
	s_waitcnt lgkmcnt(0)
	v_writelane_b32 v252, s4, 4
	s_nop 1
	v_writelane_b32 v252, s5, 5
	v_writelane_b32 v252, s6, 6
	v_writelane_b32 v252, s7, 7
	v_writelane_b32 v252, s8, 8
	v_writelane_b32 v252, s9, 9
	v_writelane_b32 v252, s10, 10
	v_writelane_b32 v252, s11, 11
	s_add_u32 s8, s0, 0xc0
	s_addc_u32 s9, s1, 0
	v_readfirstlane_b32 s10, v202
	s_and_saveexec_b64 s[4:5], vcc
	v_lshl_add_u32 v1, v202, 2, 0
	v_add_u32_e32 v1, 0x20000, v1
	v_mov_b32_e32 v2, 0
	ds_write_b32 v1, v2
	s_or_b64 exec, exec, s[4:5]
	s_waitcnt lgkmcnt(0)
	s_barrier
	s_add_u32 s26, s68, 0xb00000
	s_getreg_b32 s3, hwreg(HW_REG_XCC_ID, 0, 4)
	s_addc_u32 s27, s69, 0
	s_and_b32 s73, s3, 15
	v_cmp_eq_u32_e64 s[96:97], 0, v202
	s_and_saveexec_b64 s[4:5], s[96:97]
	s_cbranch_execz .LBB0_5
	s_mov_b64 s[6:7], exec
	v_mbcnt_lo_u32_b32 v1, s6, 0
	v_mbcnt_hi_u32_b32 v1, s7, v1
	v_cmp_eq_u32_e32 vcc, 0, v1
	s_and_b64 s[12:13], exec, vcc
	s_mov_b64 exec, s[12:13]
	s_cbranch_execz .LBB0_5
	s_lshl_b32 s3, s73, 8
	s_bcnt1_i32_b64 s6, s[6:7]
	v_mov_b32_e32 v1, s3
	v_mov_b32_e32 v2, s6
	global_atomic_add v1, v2, s[26:27] offset:1024
	s_and_b32 s3, s2, 7
	s_lshl_b32 s3, s3, 4
	s_add_i32 s3, s3, s73
	s_lshl_b32 s3, s3, 2
	s_add_i32 s3, s3, 0x4000
	v_mov_b32_e32 v1, s3
	v_mov_b32_e32 v3, 0x2002c
	global_atomic_add v1, v2, s[26:27]
	ds_write_b32 v3, v1
	s_and_b32 s3, s2, 7
	s_mul_i32 s6, s3, 0x1400000
	s_mul_i32 s7, s3, 0x800000
	v_mov_b32_e32 v3, 0x20000
	v_mov_b32_e32 v4, s6
	v_mov_b32_e32 v5, s7
	ds_write_b32 v3, v4 offset:80
	ds_write_b32 v3, v5 offset:84

; __global__ void __launch_bounds__(512) fwd_megakernel(KArgs a) {
;     ...
;         float* ssq_attn = ssq + (size_t)SSQ_ATTN * TOK * 16; float* ssq_attn_next = ssq_attn; float* ssq_mlp = ssq + (size_t)SSQ_MLP * TOK * 16;
;         const bf16* Oattn; const bf16* Wo_t;
;         unsigned char* wbl = is_mla ? (ws + WS_WMLA + j * W_MLA_SZ) : (ws + WS_WMOBA + j * W_MOBA_SZ);
;         bf16* CQ = (bf16*)(ws + WS_CQ); bf16* CKV = (bf16*)(ws + WS_CKV); bf16* KPE = (bf16*)(ws + WS_KPE);
;         bf16* Q = (bf16*)(ws + WS_Q); bf16* KN = (bf16*)(ws + WS_KN); bf16* VRAW = (bf16*)(ws + WS_VRAW);
;         bf16* QKV = (bf16*)(ws + WS_QKV);
;         float* ssq_cq = ssq + (size_t)SSQ_CQ * TOK * 16; float* ssq_ckv = ssq + (size_t)SSQ_CKV * TOK * 16;
.Lxm2_done:
	s_or_b64 exec, exec, s[0:1]
	s_add_u32 s0, s68, 0x1f400000
	s_addc_u32 s1, s69, 0
	s_add_u32 s76, s68, 0x200000
	s_addc_u32 s77, s69, 0
	s_add_u32 s78, s68, 0x600000
	s_addc_u32 s79, s69, 0
	s_add_u32 s62, s68, 0xa00000
	s_addc_u32 s63, s69, 0
	s_add_u32 s66, s68, 0xa80000
	s_addc_u32 s67, s69, 0
	s_mov_b64 s[4:5], s[68:69]
	s_add_u32 s68, s4, 0x6800000
	v_writelane_b32 v252, s0, 30
	s_addc_u32 s69, s5, 0
	v_mov_b32_e32 v181, 0
	v_writelane_b32 v252, s1, 31
	s_add_u32 s0, s4, 0x1f600000
	s_addc_u32 s1, s5, 0
	v_writelane_b32 v252, s0, 32
	v_mov_b32_e32 v204, 0x358637bd
	v_mov_b32_e32 v205, 0x260
	v_writelane_b32 v252, s1, 33
	s_add_u32 s0, s4, 0xcc80000
	s_addc_u32 s1, s5, 0
	v_writelane_b32 v252, s0, 34
	v_mov_b32_e32 v182, 0x43000000
	v_mbcnt_hi_u32_b32 v206, -1, v76
	v_writelane_b32 v252, s1, 35
	s_add_u32 s0, s4, 0xcf80000
	s_addc_u32 s1, s5, 0
	s_add_u32 s86, s4, 0xcc00000
	s_addc_u32 s87, s5, 0
	s_add_u32 s88, s4, 0xa800000
	s_addc_u32 s89, s5, 0
	s_add_u32 s90, s4, 0xb400000
	s_addc_u32 s91, s5, 0
	s_add_u32 s92, s4, 0xbc00000
	v_writelane_b32 v252, s0, 36
	s_addc_u32 s93, s5, 0
	v_mov_b32_e32 v207, 0xff800000
	v_writelane_b32 v252, s1, 37
	s_add_u32 s0, s4, 0x1fa00000
	s_addc_u32 s1, s5, 0
	v_writelane_b32 v252, s0, 38
	v_mov_b32_e32 v208, 0x139fc
	v_mov_b32_e32 v209, 0xf149f2ca
	v_writelane_b32 v252, s1, 39
	s_add_u32 s0, s4, 0x1f800000
	s_addc_u32 s1, s5, 0
	v_writelane_b32 v252, s0, 40
	s_cmpk_lt_i32 s2, 0x180
	s_movk_i32 s36, 0x300
	v_writelane_b32 v252, s1, 41
	s_cselect_b64 s[0:1], -1, 0
	v_writelane_b32 v252, s0, 42
	s_ashr_i32 s3, s2, 31
	s_ashr_i32 s33, s84, 31
	v_writelane_b32 v252, s1, 43
	s_lshr_b32 s0, s3, 29
	s_add_i32 s0, s2, s0
	s_ashr_i32 s13, s0, 3
	s_and_b32 s0, s0, -8
	s_sub_i32 s14, s2, s0
	s_add_u32 s80, s4, 0xb00200
	s_addc_u32 s81, s5, 0
	s_add_u32 s16, s4, 0xb00400
	s_addc_u32 s17, s5, 0
	s_add_u32 s18, s4, 0xb00500
	s_addc_u32 s19, s5, 0
	s_add_u32 s64, s4, 0xb00600
	s_addc_u32 s65, s5, 0
	s_add_u32 s0, s4, 0xb00700
	s_addc_u32 s1, s5, 0
	v_writelane_b32 v252, s0, 44
	s_mov_b32 s51, 0
	s_mov_b64 s[58:59], 0x80
	v_writelane_b32 v252, s1, 45
	s_add_u32 s0, s4, 0xb00800
	s_addc_u32 s1, s5, 0
	v_writelane_b32 v252, s0, 46
	s_mov_b32 s94, 0x3dd53b94
	s_nop 0
	v_writelane_b32 v252, s1, 47
	s_add_u32 s0, s4, 0xb00900
	s_addc_u32 s1, s5, 0
	v_writelane_b32 v252, s0, 48
	s_nop 1
	v_writelane_b32 v252, s1, 49
	s_add_u32 s0, s4, 0xb00a00
	s_addc_u32 s1, s5, 0
	v_writelane_b32 v252, s0, 50
	s_nop 1
	v_writelane_b32 v252, s1, 51
	s_add_u32 s0, s4, 0xb00b00
	s_addc_u32 s1, s5, 0
	v_writelane_b32 v252, s0, 52
	s_nop 1
	v_writelane_b32 v252, s1, 53
	s_add_u32 s0, s4, 0xb00c00
	s_addc_u32 s1, s5, 0
	v_writelane_b32 v252, s0, 54
	s_nop 1
	v_writelane_b32 v252, s1, 55
	s_add_u32 s0, s4, 0xb00d00
	s_addc_u32 s1, s5, 0
	v_writelane_b32 v252, s0, 56
	s_nop 1
	v_writelane_b32 v252, s1, 57
	s_add_u32 s0, s4, 0xb00e00
	s_addc_u32 s1, s5, 0
	v_writelane_b32 v252, s0, 58
	s_nop 1
	v_writelane_b32 v252, s1, 59
	s_add_u32 s0, s4, 0xb00f00
	s_addc_u32 s1, s5, 0
	v_writelane_b32 v252, s0, 60
	s_nop 1
	v_writelane_b32 v252, s1, 61
	s_add_u32 s0, s4, 0xb01000
	s_addc_u32 s1, s5, 0
	v_writelane_b32 v252, s0, 62
	s_nop 1
	v_writelane_b32 v252, s1, 63
	s_add_u32 s0, s4, 0xb01100
	s_addc_u32 s1, s5, 0
	v_writelane_b32 v253, s0, 0
	s_nop 1
	v_writelane_b32 v253, s1, 1
	s_add_u32 s0, s4, 0xb01200
	s_addc_u32 s1, s5, 0
	v_writelane_b32 v253, s0, 2
	s_nop 1
	v_writelane_b32 v253, s1, 3
	s_add_u32 s0, s4, 0xb01300
	s_addc_u32 s1, s5, 0
	v_writelane_b32 v253, s0, 4
	s_cmp_eq_u32 s73, 15
	s_nop 0
	v_writelane_b32 v253, s1, 5
	s_cselect_b64 s[0:1], -1, 0
	v_writelane_b32 v253, s0, 6
	s_cmp_eq_u32 s73, 14
	s_nop 0
	v_writelane_b32 v253, s1, 7
	s_cselect_b64 s[0:1], -1, 0
	v_writelane_b32 v253, s0, 8
	s_cmp_eq_u32 s73, 13
	s_nop 0
	v_writelane_b32 v253, s1, 9
	s_cselect_b64 s[0:1], -1, 0
	v_writelane_b32 v253, s0, 10
	s_cmp_eq_u32 s73, 12
	s_nop 0
	v_writelane_b32 v253, s1, 11
	s_cselect_b64 s[0:1], -1, 0
	v_writelane_b32 v253, s0, 12
	s_cmp_eq_u32 s73, 11
	s_nop 0
	v_writelane_b32 v253, s1, 13
	s_cselect_b64 s[0:1], -1, 0
	v_writelane_b32 v253, s0, 14
	s_cmp_eq_u32 s73, 10
	s_nop 0
	v_writelane_b32 v253, s1, 15
	s_cselect_b64 s[0:1], -1, 0
	v_writelane_b32 v253, s0, 16
	s_cmp_eq_u32 s73, 9
	s_nop 0
	v_writelane_b32 v253, s1, 17
	s_cselect_b64 s[0:1], -1, 0
	v_writelane_b32 v253, s0, 18
	s_cmp_eq_u32 s73, 8
	s_nop 0
	v_writelane_b32 v253, s1, 19
	s_cselect_b64 s[0:1], -1, 0
	v_writelane_b32 v253, s0, 20
	s_cmp_eq_u32 s73, 7
	s_nop 0
	v_writelane_b32 v253, s1, 21
	s_cselect_b64 s[0:1], -1, 0
	v_writelane_b32 v253, s0, 22
	s_cmp_eq_u32 s73, 6
	s_nop 0
	v_writelane_b32 v253, s1, 23
	s_cselect_b64 s[0:1], -1, 0
	v_writelane_b32 v253, s0, 24
	s_cmp_eq_u32 s73, 5
	s_nop 0
	v_writelane_b32 v253, s1, 25
	s_cselect_b64 s[0:1], -1, 0
	v_writelane_b32 v253, s0, 26
	s_cmp_eq_u32 s73, 4
	s_nop 0
	v_writelane_b32 v253, s1, 27
	s_cselect_b64 s[0:1], -1, 0
	v_writelane_b32 v253, s0, 28
	s_cmp_eq_u32 s73, 3
	s_nop 0
	v_writelane_b32 v253, s1, 29
	s_cselect_b64 s[0:1], -1, 0
	v_writelane_b32 v253, s0, 30
	s_cmp_eq_u32 s73, 2
	s_nop 0
	v_writelane_b32 v253, s1, 31
	s_cselect_b64 s[0:1], -1, 0
	v_writelane_b32 v253, s0, 32
	s_cmp_eq_u32 s73, 1
	s_nop 0
	v_writelane_b32 v253, s1, 33
	s_cselect_b64 s[0:1], -1, 0
	v_writelane_b32 v253, s0, 34
	s_cmp_eq_u32 s73, 0
	s_nop 0
	v_writelane_b32 v253, s1, 35
	s_cselect_b64 s[0:1], -1, 0
	v_writelane_b32 v253, s0, 36
	s_nop 1
	v_writelane_b32 v253, s1, 37
	s_lshl_b32 s0, s73, 8
	s_add_u32 s0, s26, s0
	s_addc_u32 s1, s27, 0
	s_add_u32 s6, s0, 0x1400
	s_addc_u32 s7, s1, 0
	v_writelane_b32 v253, s6, 38
	s_add_u32 s0, s0, 0x2400
; __global__ void __launch_bounds__(512) fwd_megakernel(KArgs a) {
;     ...
;         float* ssq_attn = ssq + (size_t)SSQ_ATTN * TOK * 16; float* ssq_attn_next = ssq_attn; float* ssq_mlp = ssq + (size_t)SSQ_MLP * TOK * 16;
;         const bf16* Oattn; const bf16* Wo_t;
;         unsigned char* wbl = is_mla ? (ws + WS_WMLA + j * W_MLA_SZ) : (ws + WS_WMOBA + j * W_MOBA_SZ);
;         bf16* CQ = (bf16*)(ws + WS_CQ); bf16* CKV = (bf16*)(ws + WS_CKV); bf16* KPE = (bf16*)(ws + WS_KPE);
;         bf16* Q = (bf16*)(ws + WS_Q); bf16* KN = (bf16*)(ws + WS_KN); bf16* VRAW = (bf16*)(ws + WS_VRAW);
;         bf16* QKV = (bf16*)(ws + WS_QKV);
;         float* ssq_cq = ssq + (size_t)SSQ_CQ * TOK * 16; float* ssq_ckv = ssq + (size_t)SSQ_CKV * TOK * 16;
;     ...
;             att::Args AA{Q, 1536, KN, 1024, KPE, VRAW, 1024, (bf16*)(ws + WS_O_MLA), nullptr, nullptr, nullptr, a.mla_qn + j * 128, a.mla_qr + j * 64, cosT, sinT, 0.07216878364870322f * LOG2E, a.mla_kn + j * 128, a.mla_kr + j * 64, nullptr};
;             att::attn_phase<192, false>(AA, lds, vcu, G);
;             Oattn = (const bf16*)(ws + WS_O_MLA); Wo_t = (const bf16*)(wbl + W_MLA_O);
;         } else {
;             att::Args AA{QKV, 3072, QKV + 1024, 3072, nullptr, QKV + 2048, 3072, (bf16*)(ws + WS_O_MOBA), a.pos, lutG, kmeanG, a.moba_qn + j * 128, nullptr, nullptr, nullptr, 0.08838834764831845f * LOG2E, a.moba_kn + j * 128, nullptr, a.relb};
;             att::attn_phase<128, true>(AA, lds, vcu, G);
;             Oattn = (const bf16*)(ws + WS_O_MOBA); Wo_t = (const bf16*)(wbl + W_MOBA_O);
	s_addc_u32 s1, s1, 0
	v_writelane_b32 v253, s7, 39
	v_writelane_b32 v253, s0, 40
	s_nop 1
	v_writelane_b32 v253, s1, 41
	s_add_u32 s0, s4, 0xb03400
	s_addc_u32 s1, s5, 0
	v_writelane_b32 v253, s0, 42
	s_nop 1
	v_writelane_b32 v253, s1, 43
	s_add_u32 s0, s4, 0xb03500
	s_addc_u32 s1, s5, 0
	v_writelane_b32 v253, s0, 44
	s_nop 1
	v_writelane_b32 v253, s1, 45
	s_lshl_b32 s0, s70, 3
	s_cmpk_lt_i32 s70, 0x1000
	v_writelane_b32 v253, s0, 46
	s_cselect_b64 s[0:1], -1, 0
	v_writelane_b32 v253, s0, 47
	s_nop 1
	v_writelane_b32 v253, s1, 48
	s_lshl_b32 s0, s84, 6
	s_cmpk_lt_i32 s2, 0x300
	v_writelane_b32 v253, s0, 49
	s_cselect_b64 s[0:1], -1, 0
	s_add_u32 s95, s4, 0xa800800
	s_addc_u32 s8, s5, 0
	s_add_u32 s9, s4, 0xa801000
	v_writelane_b32 v253, s0, 50
	s_addc_u32 s10, s5, 0
	s_nop 0
	v_writelane_b32 v253, s1, 51
	s_add_u32 s0, s4, 0xc000000
	s_addc_u32 s1, s5, 0
	v_writelane_b32 v253, s0, 52
	s_cmpk_lt_i32 s74, 0x100
	s_nop 0
	v_writelane_b32 v253, s1, 53
	s_cselect_b64 s[0:1], -1, 0
	v_writelane_b32 v253, s0, 54
	s_nop 1
	v_writelane_b32 v253, s1, 55
	s_add_u32 s0, s4, 0xc400000
	v_writelane_b32 v253, s4, 56
	s_addc_u32 s1, s5, 0
	s_cmpk_lt_i32 s2, 0x200
	v_writelane_b32 v253, s5, 57
	v_writelane_b32 v253, s0, 58
	s_movk_i32 s4, 0x61
	s_nop 0
	v_writelane_b32 v253, s1, 59
	s_cselect_b64 s[0:1], -1, 0
	v_writelane_b32 v253, s0, 60
	s_nop 1
	v_writelane_b32 v253, s1, 61
	s_and_b32 s6, s2, 7
	s_mul_i32 s0, s6, 0x2900000
	s_add_u32 s86, s86, s0
	s_addc_u32 s87, s87, 0
	s_mul_i32 s0, s6, 0x980000
	s_add_u32 s88, s88, s0
	s_addc_u32 s89, s89, 0
	s_mul_i32 s0, s6, 0x2180000
	s_add_u32 s90, s90, s0
	s_addc_u32 s91, s91, 0
	s_mul_i32 s0, s6, 0x2180000
	s_add_u32 s92, s92, s0
	s_addc_u32 s93, s93, 0
	s_mul_i32 s0, s6, 0x1180000
	s_add_u32 s95, s95, s0
	s_addc_u32 s8, s8, 0
	s_mul_i32 s0, s6, 0x1180000
	s_add_u32 s9, s9, s0
	s_addc_u32 s10, s10, 0
	v_readlane_b32 s0, v252, 34
	v_readlane_b32 s1, v252, 35
	s_mul_i32 s7, s6, 0x2680000
	s_nop 0
	s_add_u32 s0, s0, s7
	s_addc_u32 s1, s1, 0
	v_writelane_b32 v252, s0, 34
	v_writelane_b32 v252, s1, 35
	v_readlane_b32 s0, v252, 36
	v_readlane_b32 s1, v252, 37
	s_mul_i32 s7, s6, 0x2780000
	s_nop 0
	s_add_u32 s0, s0, s7
	s_addc_u32 s1, s1, 0
	v_writelane_b32 v252, s0, 36
	v_writelane_b32 v252, s1, 37
	v_readlane_b32 s0, v253, 52
	v_readlane_b32 s1, v253, 53
	s_mul_i32 s7, s6, 0x2180000
	s_nop 0
	s_add_u32 s0, s0, s7
	s_addc_u32 s1, s1, 0
	v_writelane_b32 v253, s0, 52
	v_writelane_b32 v253, s1, 53
	v_readlane_b32 s0, v253, 58
	v_readlane_b32 s1, v253, 59
	s_mul_i32 s7, s6, 0x2180000
	s_nop 0
	s_add_u32 s0, s0, s7
	s_addc_u32 s1, s1, 0
	v_writelane_b32 v253, s0, 58
	v_writelane_b32 v253, s1, 59
	s_mul_i32 s0, s6, 0x800000
	s_nop 0
	v_writelane_b32 v255, s0, 17
	s_lshl_b32 s0, s14, 6
	s_cmp_lt_i32 s14, 0
	s_mul_i32 s1, s14, 0x41
	s_cselect_b32 s0, s1, s0
	s_cselect_b32 s1, 49, 48
	s_mul_i32 s1, s14, s1
	s_cselect_b32 s4, s4, 0x60
	s_add_i32 s1, s1, s13
	s_mul_hi_i32 s5, s1, 0x2aaaaaab
	s_lshr_b32 s6, s5, 31
	s_ashr_i32 s5, s5, 2
	s_add_i32 s5, s5, s6
	s_mul_i32 s6, s5, 24
	s_sub_i32 s1, s1, s6
	s_bfe_i32 s6, s1, 0x80000
	s_bfe_u32 s6, s6, 0x3000c
	s_add_i32 s6, s1, s6
	s_mul_i32 s4, s14, s4
	s_and_b32 s7, s6, 0xf8
	s_add_i32 s4, s4, s13
	s_sub_i32 s1, s1, s7
	s_mul_hi_i32 s7, s4, 0x2aaaaaab
	s_lshr_b32 s11, s7, 31
	s_ashr_i32 s7, s7, 3
	s_add_i32 s7, s7, s11
	s_mul_i32 s11, s7, 48
	s_sub_i32 s4, s4, s11
	s_bfe_i32 s11, s4, 0x80000
	s_bfe_u32 s11, s11, 0x3000c
	s_add_i32 s11, s4, s11
	s_and_b32 s12, s11, 0xf8
	s_sub_i32 s4, s4, s12
	s_lshl_b32 s7, s7, 3
	s_sext_i32_i8 s4, s4
	s_add_i32 s0, s0, s13
	s_add_i32 s15, s7, s4
	s_ashr_i32 s4, s0, 31
	s_lshr_b32 s4, s4, 27
	s_add_i32 s4, s0, s4
	s_and_b32 s7, s4, 0xffe0
	s_sub_i32 s0, s0, s7
	s_bfe_i32 s7, s0, 0x80000
	s_bfe_u32 s7, s7, 0x3000c
	s_add_i32 s7, s0, s7
	s_and_b32 s12, s7, 0xf8
	s_sub_i32 s12, s0, s12
	s_lshl_b32 s0, s5, 3
	s_sext_i32_i8 s1, s1
	s_bfe_i32 s5, s6, 0x80000
	s_add_i32 s6, s0, s1
;     __host__ __device__ bool next(int i, Unit& u) const {
;         const long L = (long)i * G + c; if (L >= nwg) return false;
;         int wgid = (int)L; { const int q = nwg / NXCD, r = nwg % NXCD, xcd = wgid % NXCD, off = wgid / NXCD; wgid = (xcd < r ? xcd * (q + 1) : r * (q + 1) + (xcd - r) * q) + off; }
;         const int nig = WGM * nN, gid = wgid / nig, fm = gid * WGM, gsz = (nM - fm) < WGM ? (nM - fm) : WGM;
;         u.pm = fm + ((wgid % nig) % gsz); u.pn = (wgid % nig) / gsz; return true;
;     }
;     __host__ __device__ bool next(int i, Unit& u) const { const int nr = nwg / G; if (i >= nr) return false; return StaticOrder::next(nr - 1 - i, u); }
	s_bfe_i32 s0, s11, 0x80000
	s_sext_i32_i16 s0, s0
	v_writelane_b32 v253, s13, 62
	s_ashr_i32 s1, s0, 3
	s_lshr_b32 s0, s0, 3
	v_writelane_b32 v253, s1, 63
	s_bfe_i64 s[0:1], s[0:1], 0x100000
	v_writelane_b32 v254, s0, 0
	s_sext_i32_i16 s5, s5
	s_movk_i32 s11, 0xc00
	v_writelane_b32 v254, s1, 1
	s_ashr_i32 s0, s4, 5
	s_bfe_i32 s1, s7, 0x80000
	s_lshl_b32 s0, s0, 3
	s_sext_i32_i16 s4, s1
	s_sext_i32_i8 s1, s12
	s_add_i32 s12, s0, s1
	s_ashr_i32 s0, s5, 3
	v_writelane_b32 v254, s0, 2
	s_lshr_b32 s0, s5, 3
	s_bfe_i64 s[0:1], s[0:1], 0x100000
	s_lshl_b64 s[0:1], s[0:1], 19
	v_writelane_b32 v254, s0, 3
	s_ashr_i32 s7, s6, 31
	s_nop 0
	v_writelane_b32 v254, s1, 4
	v_writelane_b32 v254, s15, 5
	s_ashr_i32 s0, s15, 31
	v_writelane_b32 v254, s0, 6
	s_ashr_i32 s0, s4, 3
	v_writelane_b32 v254, s0, 7
	s_lshr_b32 s0, s4, 3
	s_mov_b32 s4, s6
	v_writelane_b32 v254, s4, 8
	s_nop 1
	v_writelane_b32 v254, s5, 9
	s_lshl_b64 s[4:5], s[6:7], 19
	s_add_u32 s4, s68, s4
	s_addc_u32 s5, s69, s5
	s_add_u32 s6, s4, 0x40000
	v_writelane_b32 v254, s4, 10
	s_addc_u32 s7, s5, 0
	s_abs_i32 s1, s84
	v_cvt_f32_u32_e32 v0, s1
	v_writelane_b32 v254, s5, 11
	v_writelane_b32 v254, s6, 12
	s_sub_i32 s4, 0, s1
	v_rcp_iflag_f32_e32 v0, v0
	v_writelane_b32 v254, s7, 13
	s_ashr_i32 s13, s12, 31
	v_writelane_b32 v254, s12, 14
	v_mul_f32_e32 v0, 0x4f7ffffe, v0
	v_cvt_u32_f32_e32 v0, v0
	v_writelane_b32 v254, s13, 15
	s_bfe_i64 s[6:7], s[0:1], 0x100000
	v_writelane_b32 v254, s6, 16
	v_readfirstlane_b32 s5, v0
	s_mul_i32 s4, s4, s5
	s_mul_hi_u32 s4, s5, s4
	s_add_i32 s5, s5, s4
	s_lshr_b32 s0, s5, 21
	v_writelane_b32 v254, s7, 17
	s_mul_i32 s4, s0, s1
	s_sub_i32 s4, 0x800, s4
	v_writelane_b32 v254, s14, 18
	s_lshr_b32 s5, s14, 31
	v_writelane_b32 v254, s5, 19
	s_add_i32 s5, s0, 1
	s_sub_i32 s6, s4, s1
	s_cmp_ge_u32 s4, s1
	s_cselect_b32 s0, s5, s0
	s_cselect_b32 s4, s6, s4
	s_add_i32 s5, s0, 1
	s_cmp_ge_u32 s4, s1
	s_cselect_b32 s0, s5, s0
	s_xor_b32 s0, s0, s33
	s_sub_i32 s37, s0, s33
	s_mul_i32 s1, s85, s84
	s_cmp_gt_i32 s37, 0
	s_mul_i32 s85, s1, s71
	s_cselect_b64 s[0:1], -1, 0
	v_writelane_b32 v254, s0, 20
	v_mov_b64_e32 v[0:1], 0x800
	s_movk_i32 s12, 0x140
	v_writelane_b32 v254, s1, 21
	s_add_i32 s0, s37, -1
	s_mul_i32 s1, s0, s33
	s_mul_hi_u32 s4, s0, s84
	s_add_i32 s4, s4, s1
	s_mul_i32 s0, s0, s84
	s_add_u32 s0, s0, s2
	s_addc_u32 s1, s4, s3
	s_ashr_i32 s4, s0, 31
	s_lshr_b32 s4, s4, 29
	s_add_i32 s4, s0, s4
	s_ashr_i32 s5, s4, 3
	s_and_b32 s4, s4, -8
	s_sub_i32 s4, s0, s4
	s_cmp_gt_i32 s4, -1
	v_writelane_b32 v254, s5, 22
	s_cselect_b64 s[6:7], -1, 0
	v_writelane_b32 v254, s6, 23
	s_lshl_b32 s5, s72, 3
	v_cmp_lt_i64_e64 s[0:1], s[0:1], v[0:1]
	v_writelane_b32 v254, s7, 24
	s_lshl_b32 s6, s74, 6
	v_writelane_b32 v254, s74, 25
	s_add_i32 s5, s6, s5
	v_writelane_b32 v254, s5, 26
	v_writelane_b32 v254, s0, 27
	s_mov_b64 s[74:75], s[16:17]
	s_mov_b64 s[72:73], s[18:19]
	v_writelane_b32 v254, s1, 28
	s_lshl_b32 s0, s4, 8
	v_writelane_b32 v254, s0, 29
	s_mul_i32 s0, s4, 0x101
	v_writelane_b32 v254, s0, 30
	s_add_i32 s0, s37, -2
	v_writelane_b32 v254, s0, 31
	s_lshl_b32 s0, s84, 11
	v_writelane_b32 v254, s0, 32
	s_add_i32 s0, 0, 0x20020
	v_writelane_b32 v254, s0, 33
	s_add_i32 s0, 0, 0x20024
	v_writelane_b32 v254, s0, 34
	s_add_i32 s0, 0, 0x22100
	v_writelane_b32 v254, s0, 35
	s_add_i32 s0, 0, 0x22900
	v_writelane_b32 v254, s0, 36
	v_writelane_b32 v254, s96, 37
	s_mov_b32 s14, 0xffff
	s_mov_b32 s5, 0
	v_writelane_b32 v254, s97, 38
	v_writelane_b32 v254, s76, 39
	s_nop 1
	v_writelane_b32 v254, s77, 40
	v_writelane_b32 v254, s78, 41
	s_nop 1
	v_writelane_b32 v254, s79, 42
	v_writelane_b32 v254, s80, 43
	s_nop 1
	v_writelane_b32 v254, s81, 44
	v_writelane_b32 v254, s74, 45
	s_nop 1
	v_writelane_b32 v254, s75, 46
	v_writelane_b32 v254, s72, 47
	s_nop 1
	v_writelane_b32 v254, s73, 48
	v_writelane_b32 v254, s62, 49
	s_nop 1
	v_writelane_b32 v254, s63, 50
	v_writelane_b32 v254, s64, 51
	s_nop 1
	v_writelane_b32 v254, s65, 52
	s_branch .LBB0_166

; __global__ void __launch_bounds__(512) fwd_megakernel(KArgs a) {
;     ...
;             else { g = pg8::Gemm{XB, (const bf16*)(wbl + W_MOBA_QKV), TOK, 3072, 1024};
;                 E = pg8::EpiGen<4>{ssq_attn, 16, 1.0f / 1024.0f, QKV, 3072, nullptr, nullptr, 0, nullptr, nullptr, nullptr, nullptr, a.moba_kn + j * 128, kmeanG, 2, xl}; }
;             pg8::StaticOrder S; S.init(g.M, g.N, G, bx);
;             pg8::gemm_phase<pg8::EpiGen<4>, pg8::StaticOrder, true, true>(lds, g, S, E);
.LBB0_410:
	v_writelane_b32 v254, s4, 56
	v_readlane_b32 s72, v252, 4
	v_readlane_b32 s76, v252, 8
	v_writelane_b32 v254, s5, 57
	v_writelane_b32 v254, s68, 58
	v_readlane_b32 s77, v252, 9
	v_readlane_b32 s78, v252, 10
	v_writelane_b32 v254, s69, 59
	v_writelane_b32 v254, s66, 60
	v_readlane_b32 s79, v252, 11
	v_readlane_b32 s80, v252, 30
	v_writelane_b32 v254, s67, 61
	v_readlane_b32 s74, v252, 6
	v_readlane_b32 s75, v252, 7
	v_readlane_b32 s78, v254, 41
	v_readlane_b32 s76, v254, 39
	v_readlane_b32 s64, v254, 51
	s_mov_b32 s62, 0x3a800000
	s_mov_b64 s[0:1], 0xc00
	s_mov_b64 s[42:43], 0
	s_mov_b32 s13, 12
	s_movk_i32 s34, 0x400
	v_readlane_b32 s60, v255, 17
	s_nop 1
	s_add_u32 s60, s88, s60
	s_addc_u32 s61, s89, 0
	v_readlane_b32 s81, v252, 31
	v_readlane_b32 s73, v252, 5
	v_readlane_b32 s79, v254, 42
	v_readlane_b32 s77, v254, 40
	s_mov_b64 s[30:31], s[74:75]
	v_readlane_b32 s65, v254, 52
	s_branch .LBB0_490

; __device__ __forceinline__ unsigned cvt_pk_bf16(float lo, float hi) { f32x2 v = {lo, hi}; bf16x2_t b = __builtin_convertvector(v, bf16x2_t); return __builtin_bit_cast(unsigned, b); }
;     __device__ __forceinline__ void operator()(const f32x4 (&acc)[2][2][4][2], const Unit& u, int wr, int wc, int fr, int fq) const {
;     ...
;                 if (MODE == 0 || MODE == 1) {
; #pragma unroll
;                     for (int bj = 0; bj < 2; ++bj) {
;                         const int hf = 2 * u.pn + bj;
;                         bf16_t* dst;
;                         if (split2) dst = ((hf & 1) ? O2 : O) + (size_t)row * ldc + (hf >> 1) * 128 + wc * 32 + 8 * fq;
;                         else dst = O + (size_t)row * ldc + hf * 128 + wc * 32 + 8 * fq;
;                         f32x4 v0 = acc[ai][bj][m][0] * sc, v1 = acc[ai][bj][m][1] * sc;
;                         if (MODE == 1) {
; #pragma unroll
;                             for (int e = 0; e < 4; ++e) { float a = fmaxf(v0[e], 0.f), b = fmaxf(v1[e], 0.f); v0[e] = a * a; v1[e] = b * b; }
;                         }
;                         u32x4 w; w.x = cvt_pk_bf16(v0[0], v0[1]); w.y = cvt_pk_bf16(v0[2], v0[3]); w.z = cvt_pk_bf16(v1[0], v1[1]); w.w = cvt_pk_bf16(v1[2], v1[3]);
;                         if (MODE == 1) asm volatile("global_store_dwordx4 %0, %1, off sc1\n\ts_nop 1" :: "v"(dst), "v"(w) : "memory");
;                         else *(u32x4*)dst = w;
;                     }
.LBB0_485:
	s_lshl_b32 s6, s49, 8
	v_lshl_add_u32 v143, s52, 8, v140
	v_mov_b32_e32 v214, 0x20000
	ds_read_b32 v216, v214 offset:80
	v_mov_b32_e32 v217, 0
	s_waitcnt lgkmcnt(0)
	v_lshl_add_u64 v[144:145], s[88:89], 0, v[216:217]
	s_ashr_i32 s7, s6, 31
	v_mad_i64_i32 v[146:147], s[46:47], v143, s11, v[144:145]
	s_lshl_b64 s[6:7], s[6:7], 1
	v_cvt_pk_bf16_f32 v116, v116, v117
	v_cvt_pk_bf16_f32 v117, v118, v119
	v_cvt_pk_bf16_f32 v118, v112, v113
	v_or_b32_e32 v112, 16, v143
	v_lshl_add_u64 v[146:147], v[146:147], 0, s[6:7]
	v_mad_i64_i32 v[112:113], s[46:47], v112, s11, v[144:145]
	v_cvt_pk_bf16_f32 v100, v100, v101
	v_cvt_pk_bf16_f32 v101, v102, v103
	v_cvt_pk_bf16_f32 v102, v96, v97
	v_or_b32_e32 v96, 32, v143
	v_lshl_add_u64 v[146:147], v[146:147], 0, s[50:51]
	v_lshl_add_u64 v[112:113], v[112:113], 0, s[6:7]
	v_mad_i64_i32 v[96:97], s[46:47], v96, s11, v[144:145]
	v_cvt_pk_bf16_f32 v84, v84, v85
	v_cvt_pk_bf16_f32 v85, v86, v87
	v_cvt_pk_bf16_f32 v86, v80, v81
	v_or_b32_e32 v80, 48, v143
	v_lshl_add_u64 v[146:147], v[146:147], 0, v[180:181]
	v_cvt_pk_bf16_f32 v120, v120, v121
	v_cvt_pk_bf16_f32 v121, v122, v123
	v_cvt_pk_bf16_f32 v122, v124, v125
	v_cvt_pk_bf16_f32 v123, v126, v127
	v_cvt_pk_bf16_f32 v119, v114, v115
	v_lshl_add_u64 v[112:113], v[112:113], 0, s[50:51]
	v_lshl_add_u64 v[96:97], v[96:97], 0, s[6:7]
	v_mad_i64_i32 v[80:81], s[46:47], v80, s11, v[144:145]
	v_cvt_pk_bf16_f32 v68, v68, v69
	v_cvt_pk_bf16_f32 v69, v70, v71
	v_cvt_pk_bf16_f32 v70, v64, v65
	v_add_u32_e32 v64, 0x80, v143
	global_store_dwordx4 v[146:147], v[120:123], off
	global_store_dwordx4 v[146:147], v[116:119], off offset:256
	v_lshl_add_u64 v[112:113], v[112:113], 0, v[180:181]
	v_cvt_pk_bf16_f32 v108, v108, v109
	v_cvt_pk_bf16_f32 v109, v110, v111
	v_cvt_pk_bf16_f32 v110, v104, v105
	v_cvt_pk_bf16_f32 v111, v106, v107
	v_cvt_pk_bf16_f32 v103, v98, v99
	v_lshl_add_u64 v[96:97], v[96:97], 0, s[50:51]
	v_lshl_add_u64 v[80:81], v[80:81], 0, s[6:7]
	v_mad_i64_i32 v[64:65], s[46:47], v64, s11, v[144:145]
	v_cvt_pk_bf16_f32 v52, v52, v53
	v_cvt_pk_bf16_f32 v53, v54, v55
	v_cvt_pk_bf16_f32 v54, v48, v49
	v_add_u32_e32 v48, 0x90, v143
	global_store_dwordx4 v[112:113], v[108:111], off
	global_store_dwordx4 v[112:113], v[100:103], off offset:256
	v_lshl_add_u64 v[96:97], v[96:97], 0, v[180:181]
	v_cvt_pk_bf16_f32 v92, v92, v93
	v_cvt_pk_bf16_f32 v93, v94, v95
	v_cvt_pk_bf16_f32 v94, v88, v89
	v_cvt_pk_bf16_f32 v95, v90, v91
	v_cvt_pk_bf16_f32 v87, v82, v83
	v_lshl_add_u64 v[80:81], v[80:81], 0, s[50:51]
	v_lshl_add_u64 v[64:65], v[64:65], 0, s[6:7]
	v_mad_i64_i32 v[48:49], s[46:47], v48, s11, v[144:145]
	v_cvt_pk_bf16_f32 v36, v36, v37
	v_cvt_pk_bf16_f32 v37, v38, v39
	v_cvt_pk_bf16_f32 v38, v32, v33
	v_add_u32_e32 v32, 0xa0, v143
	global_store_dwordx4 v[96:97], v[92:95], off
	global_store_dwordx4 v[96:97], v[84:87], off offset:256
	v_lshl_add_u64 v[80:81], v[80:81], 0, v[180:181]
	v_cvt_pk_bf16_f32 v76, v76, v77
	v_cvt_pk_bf16_f32 v77, v78, v79
	v_cvt_pk_bf16_f32 v78, v72, v73
	v_cvt_pk_bf16_f32 v79, v74, v75
	v_cvt_pk_bf16_f32 v71, v66, v67
	v_lshl_add_u64 v[64:65], v[64:65], 0, s[50:51]
	v_lshl_add_u64 v[48:49], v[48:49], 0, s[6:7]
	v_mad_i64_i32 v[32:33], s[46:47], v32, s11, v[144:145]
	v_cvt_pk_bf16_f32 v20, v20, v21
	v_cvt_pk_bf16_f32 v21, v22, v23
	v_cvt_pk_bf16_f32 v22, v16, v17
	v_add_u32_e32 v16, 0xb0, v143
	global_store_dwordx4 v[80:81], v[76:79], off
	global_store_dwordx4 v[80:81], v[68:71], off offset:256
	v_lshl_add_u64 v[64:65], v[64:65], 0, v[180:181]
	v_cvt_pk_bf16_f32 v60, v60, v61
	v_cvt_pk_bf16_f32 v61, v62, v63
	v_cvt_pk_bf16_f32 v62, v56, v57
	v_cvt_pk_bf16_f32 v63, v58, v59
	v_cvt_pk_bf16_f32 v55, v50, v51
	v_lshl_add_u64 v[48:49], v[48:49], 0, s[50:51]
	v_lshl_add_u64 v[32:33], v[32:33], 0, s[6:7]
	v_mad_i64_i32 v[16:17], s[46:47], v16, s11, v[144:145]
	global_store_dwordx4 v[64:65], v[60:63], off
	global_store_dwordx4 v[64:65], v[52:55], off offset:256
	v_lshl_add_u64 v[48:49], v[48:49], 0, v[180:181]
	v_cvt_pk_bf16_f32 v44, v44, v45
	v_cvt_pk_bf16_f32 v45, v46, v47
	v_cvt_pk_bf16_f32 v46, v40, v41
	v_cvt_pk_bf16_f32 v47, v42, v43
	v_cvt_pk_bf16_f32 v39, v34, v35
	v_lshl_add_u64 v[32:33], v[32:33], 0, s[50:51]
	v_lshl_add_u64 v[16:17], v[16:17], 0, s[6:7]
	global_store_dwordx4 v[48:49], v[44:47], off
	global_store_dwordx4 v[48:49], v[36:39], off offset:256
	v_lshl_add_u64 v[32:33], v[32:33], 0, v[180:181]
	v_cvt_pk_bf16_f32 v28, v28, v29
	v_cvt_pk_bf16_f32 v29, v30, v31
	v_cvt_pk_bf16_f32 v30, v24, v25
	v_cvt_pk_bf16_f32 v31, v26, v27
	v_cvt_pk_bf16_f32 v23, v18, v19
	v_lshl_add_u64 v[16:17], v[16:17], 0, s[50:51]
	global_store_dwordx4 v[32:33], v[28:31], off
	global_store_dwordx4 v[32:33], v[20:23], off offset:256
	v_lshl_add_u64 v[16:17], v[16:17], 0, v[180:181]
	v_cvt_pk_bf16_f32 v12, v12, v13
	v_cvt_pk_bf16_f32 v13, v14, v15
	v_cvt_pk_bf16_f32 v14, v8, v9
	v_cvt_pk_bf16_f32 v15, v10, v11
	v_cvt_pk_bf16_f32 v4, v4, v5
	v_cvt_pk_bf16_f32 v5, v6, v7
	v_cvt_pk_bf16_f32 v6, v0, v1
	v_cvt_pk_bf16_f32 v7, v2, v3
	global_store_dwordx4 v[16:17], v[12:15], off
	global_store_dwordx4 v[16:17], v[4:7], off offset:256
	s_and_b64 vcc, exec, s[38:39]
	s_mov_b64 s[6:7], -1
	s_cbranch_vccnz .LBB0_472
	s_andn2_b64 vcc, exec, s[30:31]
	s_cbranch_vccnz .LBB0_471
	s_barrier
	s_branch .LBB0_471

; __device__ __forceinline__ float bf2f(unsigned short v) { return __uint_as_float(((unsigned)v) << 16); }
; template <int DQK, bool MOBA>
; __device__ __forceinline__ void attn_unit(const Args& A, int b, int h, int qb, lptr lds) {
;     ...
;     const int tid = tid_o, lane = tid & 63, r32 = lane & 31, hi = lane >> 5;
;     const int wid = __builtin_amdgcn_readfirstlane(tid >> 6);
;     const int tb = b * SEQ, q0 = qb * 256, own = qb, bh = b * NH + h;
;     const int qrow = tb + q0 + wid * 32 + r32;
;     const int qrel = wid * 32 + r32;
;     __syncthreads();
;     bf16x8 qf[NS];
;     {
;         const bf16* qp = A.Q + (size_t)qrow * A.q_pitch + h * DQK + 8 * hi;
; #pragma unroll
;         for (int s = 0; s < NS; ++s) qf[s] = *(const bf16x8*)(qp + 16 * s);
;     }
;     {
;         float ssn = 0.f;
; #pragma unroll
;         for (int s = 0; s < 8; ++s)
; #pragma unroll
;             for (int e = 0; e < 8; ++e) { const float f = bf2f((unsigned short)qf[s][e]); ssn += f * f; }
;         ssn += __shfl_xor(ssn, 32);
.LBB0_761:
	s_lshl_b32 s0, s53, 2
	s_add_i32 s0, s0, s50
	s_ashr_i32 s1, s0, 31
	s_lshr_b32 s4, s1, 29
	s_add_i32 s4, s0, s4
	s_and_b32 s5, s4, -8
	v_mov_b32_e32 v162, v202
	s_sub_i32 s19, s0, s5
	s_lshl_b32 s4, s4, 8
	v_readfirstlane_b32 s5, v162
	s_and_b32 s70, s4, 0xfffff800
	s_lshl_b32 s17, s18, 8
	s_ashr_i32 s71, s5, 1
	s_add_i32 s42, s17, s70
	s_andn2_b32 s71, s71, 31
	v_and_b32_e32 v83, 31, v162
	s_add_i32 s4, s71, s42
	v_or_b32_e32 v160, s4, v83
	v_mov_b32_e32 v188, 0x20000
	ds_read_b32 v186, v188 offset:84
	v_mov_b32_e32 v187, 0
	s_waitcnt lgkmcnt(0)
	v_lshl_add_u64 v[0:1], s[88:89], 0, v[186:187]
	s_movk_i32 s4, 0x1800
	s_lshl_b32 s46, s19, 7
	v_and_b32_e32 v3, 64, v206
	v_bfe_u32 v82, v162, 5, 1
	v_mad_i64_i32 v[0:1], s[4:5], v160, s4, v[0:1]
	s_ashr_i32 s47, s46, 31
	v_xor_b32_e32 v2, 32, v206
	v_add_u32_e32 v89, 64, v3
	v_lshl_add_u64 v[0:1], s[46:47], 1, v[0:1]
	v_lshlrev_b32_e32 v36, 4, v82
	v_mov_b32_e32 v37, v181
	v_cmp_lt_i32_e32 vcc, v2, v89
	v_lshl_add_u64 v[0:1], v[0:1], 0, v[36:37]
	v_and_b32_e32 v37, 32, v162
	v_cndmask_b32_e32 v2, v206, v2, vcc
	s_barrier
	v_mov_b32_e32 v230, 0x14a00
	v_mov_b32_e32 v229, 0x40000000
	ds_write_b32 v230, v209
	global_load_dwordx4 v[44:47], v[0:1], off offset:224
	global_load_dwordx4 v[52:55], v[0:1], off offset:192
	global_load_dwordx4 v[60:63], v[0:1], off offset:160
	global_load_dwordx4 v[68:71], v[0:1], off offset:128
	global_load_dwordx4 v[76:79], v[0:1], off offset:96
	global_load_dwordx4 v[84:87], v[0:1], off offset:64
	v_lshlrev_b32_e32 v170, 2, v2
	global_load_dwordx4 v[28:31], v37, s[30:31] offset:16
	global_load_dwordx4 v[32:35], v37, s[30:31]
	global_load_dwordx4 v[90:93], v[0:1], off
	global_load_dwordx4 v[94:97], v[0:1], off offset:32
	global_load_dwordx4 v[20:23], v37, s[30:31] offset:80
	global_load_dwordx4 v[24:27], v37, s[30:31] offset:64
	global_load_dwordx4 v[12:15], v37, s[30:31] offset:144
	global_load_dwordx4 v[16:19], v37, s[30:31] offset:128
	global_load_dwordx4 v[4:7], v37, s[30:31] offset:208
	global_load_dwordx4 v[8:11], v37, s[30:31] offset:192
	global_load_dwordx4 v[0:3], v37, s[30:31] offset:256
	s_lshl_b64 s[0:1], s[0:1], 12
	s_add_u32 s0, s66, s0
	v_ashrrev_i32_e32 v163, 31, v162
	s_addc_u32 s1, s67, s1
	v_ashrrev_i32_e32 v161, 31, v160
	s_cmp_gt_u32 s18, 3
	s_waitcnt vmcnt(8)
	v_and_b32_e32 v175, 0xffff0000, v90
	v_lshlrev_b32_e32 v174, 16, v90
	v_and_b32_e32 v169, 0xffff0000, v91
	v_lshlrev_b32_e32 v168, 16, v91
	v_pk_mul_f32 v[90:91], v[174:175], v[174:175]
	v_pk_mul_f32 v[172:173], v[168:169], v[168:169]
	v_add_f32_e32 v88, v90, v91
	v_and_b32_e32 v167, 0xffff0000, v92
	v_lshlrev_b32_e32 v166, 16, v92
	v_add_f32_e32 v88, v172, v88
	v_and_b32_e32 v165, 0xffff0000, v93
	v_lshlrev_b32_e32 v164, 16, v93
	v_pk_mul_f32 v[92:93], v[166:167], v[166:167]
	v_add_f32_e32 v88, v173, v88
	v_add_f32_e32 v88, v92, v88
	v_pk_mul_f32 v[148:149], v[164:165], v[164:165]
	v_add_f32_e32 v88, v93, v88
	s_waitcnt vmcnt(7)
	v_and_b32_e32 v159, 0xffff0000, v94
	v_lshlrev_b32_e32 v158, 16, v94
	v_add_f32_e32 v88, v148, v88
	v_and_b32_e32 v157, 0xffff0000, v95
	v_lshlrev_b32_e32 v156, 16, v95
	v_pk_mul_f32 v[94:95], v[158:159], v[158:159]
	v_add_f32_e32 v88, v149, v88
	v_add_f32_e32 v88, v94, v88
	v_pk_mul_f32 v[146:147], v[156:157], v[156:157]
	v_add_f32_e32 v88, v95, v88
	v_and_b32_e32 v155, 0xffff0000, v96
	v_lshlrev_b32_e32 v154, 16, v96
	v_add_f32_e32 v88, v146, v88
	v_and_b32_e32 v153, 0xffff0000, v97
	v_lshlrev_b32_e32 v152, 16, v97
	v_pk_mul_f32 v[96:97], v[154:155], v[154:155]
	v_add_f32_e32 v88, v147, v88
	v_add_f32_e32 v88, v96, v88
	v_pk_mul_f32 v[144:145], v[152:153], v[152:153]
	v_add_f32_e32 v88, v97, v88
	v_and_b32_e32 v151, 0xffff0000, v84
	v_lshlrev_b32_e32 v150, 16, v84
	v_add_f32_e32 v88, v144, v88
	v_and_b32_e32 v141, 0xffff0000, v85
	v_lshlrev_b32_e32 v140, 16, v85
	v_pk_mul_f32 v[84:85], v[150:151], v[150:151]
	v_add_f32_e32 v88, v145, v88
	v_add_f32_e32 v84, v84, v88
	v_pk_mul_f32 v[142:143], v[140:141], v[140:141]
	v_add_f32_e32 v84, v85, v84
	v_and_b32_e32 v81, 0xffff0000, v86
	v_lshlrev_b32_e32 v80, 16, v86
	v_add_f32_e32 v84, v142, v84
	v_and_b32_e32 v39, 0xffff0000, v47
	v_lshlrev_b32_e32 v38, 16, v47
	v_and_b32_e32 v41, 0xffff0000, v46
	v_lshlrev_b32_e32 v40, 16, v46
	v_and_b32_e32 v47, 0xffff0000, v55
	v_lshlrev_b32_e32 v46, 16, v55
	v_and_b32_e32 v49, 0xffff0000, v54
	v_lshlrev_b32_e32 v48, 16, v54
	v_and_b32_e32 v55, 0xffff0000, v63
	v_lshlrev_b32_e32 v54, 16, v63
	v_and_b32_e32 v57, 0xffff0000, v62
	v_lshlrev_b32_e32 v56, 16, v62
	v_and_b32_e32 v63, 0xffff0000, v71
	v_lshlrev_b32_e32 v62, 16, v71
	v_and_b32_e32 v65, 0xffff0000, v70
	v_lshlrev_b32_e32 v64, 16, v70
	v_and_b32_e32 v71, 0xffff0000, v79
	v_lshlrev_b32_e32 v70, 16, v79
	v_and_b32_e32 v73, 0xffff0000, v78
	v_lshlrev_b32_e32 v72, 16, v78
	v_and_b32_e32 v79, 0xffff0000, v87
	v_lshlrev_b32_e32 v78, 16, v87
	v_pk_mul_f32 v[86:87], v[80:81], v[80:81]
	v_add_f32_e32 v84, v143, v84
	v_add_f32_e32 v84, v86, v84
	v_pk_mul_f32 v[138:139], v[78:79], v[78:79]
	v_add_f32_e32 v84, v87, v84
	v_and_b32_e32 v75, 0xffff0000, v77
	v_lshlrev_b32_e32 v74, 16, v77
	v_and_b32_e32 v77, 0xffff0000, v76
	v_lshlrev_b32_e32 v76, 16, v76
	v_add_f32_e32 v84, v138, v84
	v_pk_mul_f32 v[136:137], v[76:77], v[76:77]
	v_add_f32_e32 v84, v139, v84
	v_add_f32_e32 v84, v136, v84
	v_pk_mul_f32 v[134:135], v[74:75], v[74:75]
	v_add_f32_e32 v84, v137, v84
	v_add_f32_e32 v84, v134, v84
	v_pk_mul_f32 v[132:133], v[72:73], v[72:73]
	v_add_f32_e32 v84, v135, v84
	v_add_f32_e32 v84, v132, v84
	v_pk_mul_f32 v[130:131], v[70:71], v[70:71]
	v_add_f32_e32 v84, v133, v84
	v_and_b32_e32 v67, 0xffff0000, v69
	v_lshlrev_b32_e32 v66, 16, v69
; __device__ __forceinline__ unsigned cvt_pk_bf16(float lo, float hi) { f32x2 v = {lo, hi}; bf16x2_t b = __builtin_convertvector(v, bf16x2_t); return __builtin_bit_cast(unsigned, b); }
; __device__ __forceinline__ float bf2f(unsigned short v) { return __uint_as_float(((unsigned)v) << 16); }
; template <int DQK, bool MOBA>
; __device__ __forceinline__ void attn_unit(const Args& A, int b, int h, int qb, lptr lds) {
;     ...
;         ssn += __shfl_xor(ssn, 32);
;         const float scn = __builtin_amdgcn_rsqf(ssn * (1.0f / 128.0f) + 1e-6f) * A.qscale;
; #pragma unroll
;         for (int s = 0; s < 8; ++s) {
;             const f32x4 g0 = *(const f32x4*)(A.gq_n + 16 * s + 8 * hi), g1 = *(const f32x4*)(A.gq_n + 16 * s + 8 * hi + 4);
;             u32x4 w;
;             w.x = cvt_pk_bf16(bf2f((unsigned short)qf[s][0]) * scn * g0[0], bf2f((unsigned short)qf[s][1]) * scn * g0[1]);
;             w.y = cvt_pk_bf16(bf2f((unsigned short)qf[s][2]) * scn * g0[2], bf2f((unsigned short)qf[s][3]) * scn * g0[3]);
;             w.z = cvt_pk_bf16(bf2f((unsigned short)qf[s][4]) * scn * g1[0], bf2f((unsigned short)qf[s][5]) * scn * g1[1]);
;             w.w = cvt_pk_bf16(bf2f((unsigned short)qf[s][6]) * scn * g1[2], bf2f((unsigned short)qf[s][7]) * scn * g1[3]);
;             qf[s] = __builtin_bit_cast(bf16x8, w);
;         }
;     ...
;         lut[tid] = A.lut[h * 1024 + tid]; lut[tid + 512] = A.lut[h * 1024 + tid + 512];
;         km[tid] = A.kmean[(size_t)bh * 1024 + tid]; km[tid + 512] = A.kmean[(size_t)bh * 1024 + tid + 512];
;         pq = A.pos[qrow];
	v_and_b32_e32 v69, 0xffff0000, v68
	v_lshlrev_b32_e32 v68, 16, v68
	v_add_f32_e32 v84, v130, v84
	v_pk_mul_f32 v[128:129], v[68:69], v[68:69]
	v_add_f32_e32 v84, v131, v84
	v_add_f32_e32 v84, v128, v84
	v_pk_mul_f32 v[126:127], v[66:67], v[66:67]
	v_add_f32_e32 v84, v129, v84
	v_add_f32_e32 v84, v126, v84
	v_pk_mul_f32 v[124:125], v[64:65], v[64:65]
	v_add_f32_e32 v84, v127, v84
	v_add_f32_e32 v84, v124, v84
	v_pk_mul_f32 v[122:123], v[62:63], v[62:63]
	v_add_f32_e32 v84, v125, v84
	v_and_b32_e32 v59, 0xffff0000, v61
	v_lshlrev_b32_e32 v58, 16, v61
	v_and_b32_e32 v61, 0xffff0000, v60
	v_lshlrev_b32_e32 v60, 16, v60
	v_add_f32_e32 v84, v122, v84
	v_pk_mul_f32 v[120:121], v[60:61], v[60:61]
	v_add_f32_e32 v84, v123, v84
	v_add_f32_e32 v84, v120, v84
	v_pk_mul_f32 v[118:119], v[58:59], v[58:59]
	v_add_f32_e32 v84, v121, v84
	v_add_f32_e32 v84, v118, v84
	v_pk_mul_f32 v[116:117], v[56:57], v[56:57]
	v_add_f32_e32 v84, v119, v84
	v_add_f32_e32 v84, v116, v84
	v_pk_mul_f32 v[114:115], v[54:55], v[54:55]
	v_add_f32_e32 v84, v117, v84
	v_and_b32_e32 v51, 0xffff0000, v53
	v_lshlrev_b32_e32 v50, 16, v53
	v_and_b32_e32 v53, 0xffff0000, v52
	v_lshlrev_b32_e32 v52, 16, v52
	v_add_f32_e32 v84, v114, v84
	v_pk_mul_f32 v[112:113], v[52:53], v[52:53]
	v_add_f32_e32 v84, v115, v84
	v_add_f32_e32 v84, v112, v84
	v_pk_mul_f32 v[110:111], v[50:51], v[50:51]
	v_add_f32_e32 v84, v113, v84
	v_add_f32_e32 v84, v110, v84
	v_pk_mul_f32 v[108:109], v[48:49], v[48:49]
	v_add_f32_e32 v84, v111, v84
	v_add_f32_e32 v84, v108, v84
	v_pk_mul_f32 v[106:107], v[46:47], v[46:47]
	v_add_f32_e32 v84, v109, v84
	v_and_b32_e32 v43, 0xffff0000, v45
	v_lshlrev_b32_e32 v42, 16, v45
	v_and_b32_e32 v45, 0xffff0000, v44
	v_lshlrev_b32_e32 v44, 16, v44
	v_add_f32_e32 v84, v106, v84
	v_pk_mul_f32 v[104:105], v[44:45], v[44:45]
	v_add_f32_e32 v84, v107, v84
	v_add_f32_e32 v84, v104, v84
	v_pk_mul_f32 v[102:103], v[42:43], v[42:43]
	v_add_f32_e32 v84, v105, v84
	v_add_f32_e32 v84, v102, v84
	v_pk_mul_f32 v[100:101], v[40:41], v[40:41]
	v_add_f32_e32 v84, v103, v84
	v_add_f32_e32 v84, v100, v84
	v_pk_mul_f32 v[98:99], v[38:39], v[38:39]
	v_add_f32_e32 v84, v101, v84
	v_add_f32_e32 v84, v98, v84
	v_add_f32_e32 v84, v99, v84
	ds_bpermute_b32 v85, v170, v84
	global_load_dwordx4 v[90:93], v37, s[30:31] offset:272
	global_load_dwordx4 v[94:97], v37, s[30:31] offset:336
	global_load_dwordx4 v[98:101], v37, s[30:31] offset:320
	global_load_dwordx4 v[102:105], v37, s[30:31] offset:400
	global_load_dwordx4 v[106:109], v37, s[30:31] offset:384
	global_load_dwordx4 v[142:145], v37, s[30:31] offset:464
	global_load_dwordx4 v[146:149], v37, s[30:31] offset:448
	s_waitcnt lgkmcnt(0)
	v_add_f32_e32 v84, v84, v85
	v_fmamk_f32 v84, v84, 0x3c000000, v204
	v_rsq_f32_e32 v84, v84
	s_nop 0
	v_mul_f32_e32 v88, 0x3e0293ee, v84
	v_pk_mul_f32 v[84:85], v[88:89], v[174:175] op_sel_hi:[0,1]
	v_pk_mul_f32 v[32:33], v[32:33], v[84:85]
	s_nop 0
	v_cvt_pk_bf16_f32 v112, v32, v33
	v_pk_mul_f32 v[32:33], v[88:89], v[168:169] op_sel_hi:[0,1]
	v_pk_mul_f32 v[32:33], v[34:35], v[32:33]
	s_nop 0
	v_cvt_pk_bf16_f32 v113, v32, v33
	v_pk_mul_f32 v[32:33], v[88:89], v[166:167] op_sel_hi:[0,1]
	v_pk_mul_f32 v[28:29], v[28:29], v[32:33]
	s_nop 0
	v_cvt_pk_bf16_f32 v114, v28, v29
	v_pk_mul_f32 v[28:29], v[88:89], v[164:165] op_sel_hi:[0,1]
	v_pk_mul_f32 v[28:29], v[30:31], v[28:29]
	s_nop 0
	v_cvt_pk_bf16_f32 v37, v28, v29
	v_pk_mul_f32 v[28:29], v[88:89], v[158:159] op_sel_hi:[0,1]
	s_waitcnt vmcnt(12)
	v_pk_mul_f32 v[24:25], v[24:25], v[28:29]
	v_lshrrev_b32_e32 v30, 16, v37
	v_cvt_pk_bf16_f32 v116, v24, v25
	v_pk_mul_f32 v[24:25], v[88:89], v[156:157] op_sel_hi:[0,1]
	v_pk_mul_f32 v[24:25], v[26:27], v[24:25]
	v_and_b32_e32 v29, 0xffff0000, v116
	v_cvt_pk_bf16_f32 v117, v24, v25
	v_pk_mul_f32 v[24:25], v[88:89], v[154:155] op_sel_hi:[0,1]
	v_pk_mul_f32 v[20:21], v[20:21], v[24:25]
	v_lshlrev_b32_e32 v28, 16, v116
	v_cvt_pk_bf16_f32 v118, v20, v21
	v_pk_mul_f32 v[20:21], v[88:89], v[152:153] op_sel_hi:[0,1]
	v_pk_mul_f32 v[20:21], v[22:23], v[20:21]
	v_and_b32_e32 v27, 0xffff0000, v118
	v_cvt_pk_bf16_f32 v84, v20, v21
	v_pk_mul_f32 v[20:21], v[88:89], v[150:151] op_sel_hi:[0,1]
	s_waitcnt vmcnt(10)
	v_pk_mul_f32 v[16:17], v[16:17], v[20:21]
	v_lshl_add_u64 v[20:21], v[162:163], 2, s[0:1]
	v_cvt_pk_bf16_f32 v120, v16, v17
	v_pk_mul_f32 v[16:17], v[88:89], v[140:141] op_sel_hi:[0,1]
	v_pk_mul_f32 v[16:17], v[18:19], v[16:17]
	v_lshl_add_u32 v18, s19, 10, v162
	v_cvt_pk_bf16_f32 v121, v16, v17
	v_pk_mul_f32 v[16:17], v[88:89], v[80:81] op_sel_hi:[0,1]
	v_pk_mul_f32 v[12:13], v[12:13], v[16:17]
	v_ashrrev_i32_e32 v19, 31, v18
	v_cvt_pk_bf16_f32 v122, v12, v13
	v_pk_mul_f32 v[12:13], v[88:89], v[78:79] op_sel_hi:[0,1]
	v_pk_mul_f32 v[12:13], v[14:15], v[12:13]
	v_lshl_add_u64 v[18:19], v[18:19], 2, s[62:63]
	v_cvt_pk_bf16_f32 v80, v12, v13
	v_pk_mul_f32 v[12:13], v[88:89], v[76:77] op_sel_hi:[0,1]
	s_waitcnt vmcnt(8)
	v_pk_mul_f32 v[8:9], v[8:9], v[12:13]
	global_load_dword v23, v[18:19], off
	s_nop 0
	global_load_dword v18, v[18:19], off offset:2048
	s_nop 0
	global_load_dword v19, v[20:21], off
	s_nop 0
	global_load_dword v20, v[20:21], off offset:2048
	v_cvt_pk_bf16_f32 v124, v8, v9
	v_pk_mul_f32 v[8:9], v[88:89], v[74:75] op_sel_hi:[0,1]
	v_pk_mul_f32 v[8:9], v[10:11], v[8:9]
	v_lshrrev_b32_e32 v22, 16, v84
	v_cvt_pk_bf16_f32 v125, v8, v9
	v_pk_mul_f32 v[8:9], v[88:89], v[72:73] op_sel_hi:[0,1]
	v_pk_mul_f32 v[4:5], v[4:5], v[8:9]
	v_lshrrev_b32_e32 v16, 16, v80
	v_cvt_pk_bf16_f32 v126, v4, v5
	v_pk_mul_f32 v[4:5], v[88:89], v[70:71] op_sel_hi:[0,1]
	v_pk_mul_f32 v[4:5], v[6:7], v[4:5]
	s_mov_b64 s[0:1], -1
	v_cvt_pk_bf16_f32 v81, v4, v5
	v_pk_mul_f32 v[4:5], v[88:89], v[68:69] op_sel_hi:[0,1]
	s_waitcnt vmcnt(11)
; __device__ __forceinline__ unsigned cvt_pk_bf16(float lo, float hi) { f32x2 v = {lo, hi}; bf16x2_t b = __builtin_convertvector(v, bf16x2_t); return __builtin_bit_cast(unsigned, b); }
; __device__ __forceinline__ float bf2f(unsigned short v) { return __uint_as_float(((unsigned)v) << 16); }
; template <int DQK, bool MOBA>
; __device__ __forceinline__ void attn_unit(const Args& A, int b, int h, int qb, lptr lds) {
;     ...
;             w.x = cvt_pk_bf16(bf2f((unsigned short)qf[s][0]) * scn * g0[0], bf2f((unsigned short)qf[s][1]) * scn * g0[1]);
;             w.y = cvt_pk_bf16(bf2f((unsigned short)qf[s][2]) * scn * g0[2], bf2f((unsigned short)qf[s][3]) * scn * g0[3]);
;             w.z = cvt_pk_bf16(bf2f((unsigned short)qf[s][4]) * scn * g1[0], bf2f((unsigned short)qf[s][5]) * scn * g1[1]);
;             w.w = cvt_pk_bf16(bf2f((unsigned short)qf[s][6]) * scn * g1[2], bf2f((unsigned short)qf[s][7]) * scn * g1[3]);
;             qf[s] = __builtin_bit_cast(bf16x8, w);
;         }
;     ...
;         lut[tid] = A.lut[h * 1024 + tid]; lut[tid + 512] = A.lut[h * 1024 + tid + 512];
;         km[tid] = A.kmean[(size_t)bh * 1024 + tid]; km[tid + 512] = A.kmean[(size_t)bh * 1024 + tid + 512];
;         pq = A.pos[qrow];
;         __syncthreads();
;         if (own <= 3) sel = (1u << own) - 1u;
	v_pk_mul_f32 v[0:1], v[0:1], v[4:5]
	v_lshrrev_b32_e32 v6, 16, v81
	v_cvt_pk_bf16_f32 v128, v0, v1
	v_pk_mul_f32 v[0:1], v[88:89], v[66:67] op_sel_hi:[0,1]
	v_pk_mul_f32 v[0:1], v[2:3], v[0:1]
	v_lshl_add_u64 v[2:3], v[160:161], 2, s[54:55]
	global_load_dword v171, v[2:3], off
	v_cvt_pk_bf16_f32 v129, v0, v1
	v_pk_mul_f32 v[0:1], v[88:89], v[64:65] op_sel_hi:[0,1]
	s_waitcnt vmcnt(11)
	v_pk_mul_f32 v[0:1], v[90:91], v[0:1]
	v_lshlrev_b32_e32 v15, 16, v37
	v_cvt_pk_bf16_f32 v130, v0, v1
	v_pk_mul_f32 v[0:1], v[88:89], v[62:63] op_sel_hi:[0,1]
	v_pk_mul_f32 v[0:1], v[92:93], v[0:1]
	v_lshlrev_b32_e32 v14, 16, v30
	v_cvt_pk_bf16_f32 v85, v0, v1
	v_pk_mul_f32 v[0:1], v[88:89], v[60:61] op_sel_hi:[0,1]
	s_waitcnt vmcnt(9)
	v_pk_mul_f32 v[0:1], v[98:99], v[0:1]
	v_lshrrev_b32_e32 v4, 16, v85
	v_cvt_pk_bf16_f32 v132, v0, v1
	v_pk_mul_f32 v[0:1], v[88:89], v[58:59] op_sel_hi:[0,1]
	v_pk_mul_f32 v[0:1], v[100:101], v[0:1]
	v_lshlrev_b32_e32 v13, 16, v84
	v_cvt_pk_bf16_f32 v133, v0, v1
	v_pk_mul_f32 v[0:1], v[88:89], v[56:57] op_sel_hi:[0,1]
	v_pk_mul_f32 v[0:1], v[94:95], v[0:1]
	v_lshlrev_b32_e32 v12, 16, v22
	v_cvt_pk_bf16_f32 v134, v0, v1
	v_pk_mul_f32 v[0:1], v[88:89], v[54:55] op_sel_hi:[0,1]
	v_pk_mul_f32 v[0:1], v[96:97], v[0:1]
	v_lshlrev_b32_e32 v11, 16, v80
	v_cvt_pk_bf16_f32 v86, v0, v1
	v_pk_mul_f32 v[0:1], v[88:89], v[52:53] op_sel_hi:[0,1]
	s_waitcnt vmcnt(7)
	v_pk_mul_f32 v[0:1], v[106:107], v[0:1]
	v_lshrrev_b32_e32 v17, 16, v86
	v_cvt_pk_bf16_f32 v136, v0, v1
	v_pk_mul_f32 v[0:1], v[88:89], v[50:51] op_sel_hi:[0,1]
	v_pk_mul_f32 v[0:1], v[108:109], v[0:1]
	v_lshlrev_b32_e32 v10, 16, v16
	v_cvt_pk_bf16_f32 v137, v0, v1
	v_pk_mul_f32 v[0:1], v[88:89], v[48:49] op_sel_hi:[0,1]
	v_pk_mul_f32 v[0:1], v[102:103], v[0:1]
	v_lshlrev_b32_e32 v9, 16, v81
	v_cvt_pk_bf16_f32 v138, v0, v1
	v_pk_mul_f32 v[0:1], v[88:89], v[46:47] op_sel_hi:[0,1]
	v_pk_mul_f32 v[0:1], v[104:105], v[0:1]
	v_lshlrev_b32_e32 v8, 16, v6
	v_cvt_pk_bf16_f32 v87, v0, v1
	v_pk_mul_f32 v[0:1], v[88:89], v[44:45] op_sel_hi:[0,1]
	s_waitcnt vmcnt(5)
	v_pk_mul_f32 v[0:1], v[146:147], v[0:1]
	v_lshrrev_b32_e32 v21, 16, v87
	v_cvt_pk_bf16_f32 v140, v0, v1
	v_pk_mul_f32 v[0:1], v[88:89], v[42:43] op_sel_hi:[0,1]
	v_pk_mul_f32 v[0:1], v[148:149], v[0:1]
	v_lshlrev_b32_e32 v7, 16, v85
	v_cvt_pk_bf16_f32 v141, v0, v1
	v_pk_mul_f32 v[0:1], v[88:89], v[40:41] op_sel_hi:[0,1]
	v_pk_mul_f32 v[0:1], v[142:143], v[0:1]
	v_lshlrev_b32_e32 v6, 16, v4
	v_cvt_pk_bf16_f32 v142, v0, v1
	v_pk_mul_f32 v[0:1], v[88:89], v[38:39] op_sel_hi:[0,1]
	v_pk_mul_f32 v[0:1], v[144:145], v[0:1]
	v_lshlrev_b32_e32 v5, 16, v86
	v_cvt_pk_bf16_f32 v88, v0, v1
	v_lshl_add_u32 v1, v162, 2, 0
	v_lshrrev_b32_e32 v0, 16, v88
	v_add_u32_e32 v2, 0x12a00, v1
	v_add_u32_e32 v1, 0x13a00, v1
	s_waitcnt vmcnt(3)
	ds_write2st64_b32 v2, v23, v18 offset1:8
	s_waitcnt vmcnt(1)
	ds_write2st64_b32 v1, v19, v20 offset1:8
	v_lshlrev_b32_e32 v4, 16, v17
	v_lshlrev_b32_e32 v3, 16, v87
	v_lshlrev_b32_e32 v2, 16, v21
	v_lshlrev_b32_e32 v1, 16, v88
	v_lshlrev_b32_e32 v0, 16, v0
	v_and_b32_e32 v17, 0xffff0000, v113
	v_lshlrev_b32_e32 v16, 16, v113
	v_and_b32_e32 v23, 0xffff0000, v112
	v_lshlrev_b32_e32 v22, 16, v112
	v_and_b32_e32 v21, 0xffff0000, v114
	v_lshlrev_b32_e32 v20, 16, v114
	v_and_b32_e32 v19, 0xffff0000, v117
	v_lshlrev_b32_e32 v18, 16, v117
	v_lshlrev_b32_e32 v26, 16, v118
	v_and_b32_e32 v25, 0xffff0000, v121
	v_lshlrev_b32_e32 v24, 16, v121
	v_and_b32_e32 v35, 0xffff0000, v120
	v_lshlrev_b32_e32 v34, 16, v120
	v_and_b32_e32 v33, 0xffff0000, v122
	v_lshlrev_b32_e32 v32, 16, v122
	v_and_b32_e32 v31, 0xffff0000, v125
	v_lshlrev_b32_e32 v30, 16, v125
	v_and_b32_e32 v43, 0xffff0000, v124
	v_lshlrev_b32_e32 v42, 16, v124
	v_and_b32_e32 v41, 0xffff0000, v126
	v_lshlrev_b32_e32 v40, 16, v126
	v_and_b32_e32 v39, 0xffff0000, v129
	v_lshlrev_b32_e32 v38, 16, v129
	v_and_b32_e32 v49, 0xffff0000, v128
	v_lshlrev_b32_e32 v48, 16, v128
	v_and_b32_e32 v47, 0xffff0000, v130
	v_lshlrev_b32_e32 v46, 16, v130
	v_and_b32_e32 v45, 0xffff0000, v133
	v_lshlrev_b32_e32 v44, 16, v133
	v_and_b32_e32 v55, 0xffff0000, v132
	v_lshlrev_b32_e32 v54, 16, v132
	v_and_b32_e32 v53, 0xffff0000, v134
	v_lshlrev_b32_e32 v52, 16, v134
	v_and_b32_e32 v51, 0xffff0000, v137
	v_lshlrev_b32_e32 v50, 16, v137
	v_and_b32_e32 v61, 0xffff0000, v136
	v_lshlrev_b32_e32 v60, 16, v136
	v_and_b32_e32 v59, 0xffff0000, v138
	v_lshlrev_b32_e32 v58, 16, v138
	v_and_b32_e32 v57, 0xffff0000, v141
	v_lshlrev_b32_e32 v56, 16, v141
	v_and_b32_e32 v65, 0xffff0000, v140
	v_lshlrev_b32_e32 v64, 16, v140
	v_and_b32_e32 v63, 0xffff0000, v142
	v_lshlrev_b32_e32 v62, 16, v142
	s_waitcnt lgkmcnt(0)
	s_barrier
	s_cbranch_scc0 .LBB0_769
; #define LAS __attribute__((address_space(3)))
; __device__ __forceinline__ float bf2f(unsigned short v) { return __uint_as_float(((unsigned)v) << 16); }
; template <int DQK, bool MOBA>
; __device__ __forceinline__ void attn_unit(const Args& A, int b, int h, int qb, lptr lds) {
;     ...
;             float g[7];
; #pragma unroll
;             for (int j = 0; j < 7; ++j) {
;                 float a = 0.f;
;                 if (j < own) {
; #pragma unroll
;                     for (int s = 0; s < NS; ++s) {
;                         const f32x4 k0 = *(const LAS f32x4*)(km + j * 128 + 16 * s + 8 * hi), k1 = *(const LAS f32x4*)(km + j * 128 + 16 * s + 8 * hi + 4);
;                         a += bf2f((unsigned short)qf[s][0]) * k0[0] + bf2f((unsigned short)qf[s][1]) * k0[1] + bf2f((unsigned short)qf[s][2]) * k0[2] + bf2f((unsigned short)qf[s][3]) * k0[3];
;                         a += bf2f((unsigned short)qf[s][4]) * k1[0] + bf2f((unsigned short)qf[s][5]) * k1[1] + bf2f((unsigned short)qf[s][6]) * k1[2] + bf2f((unsigned short)qf[s][7]) * k1[3];
;                     }
;                 }
;                 a += __shfl_xor(a, 32);
;                 g[j] = a;
;             }
	v_lshlrev_b32_e32 v66, 3, v82
	v_lshl_add_u32 v66, v66, 2, 0
	v_add_u32_e32 v66, 0x13a00, v66
	ds_read_b128 v[68:71], v66
	ds_read_b128 v[72:75], v66 offset:16
	s_cmp_lg_u32 s18, 4
	v_mov_b32_e32 v67, 0
	s_cselect_b64 s[4:5], -1, 0
	s_waitcnt lgkmcnt(1)
	v_mul_f32_e32 v69, v69, v23
	v_fmac_f32_e32 v69, v68, v22
	v_fmac_f32_e32 v69, v70, v16
	v_fmac_f32_e32 v69, v71, v17
	v_add_f32_e32 v68, 0, v69
	s_waitcnt lgkmcnt(0)
	v_mul_f32_e32 v69, v73, v21
	v_fmac_f32_e32 v69, v72, v20
	v_fmac_f32_e32 v69, v74, v15
	v_fmac_f32_e32 v69, v75, v14
	v_add_f32_e32 v72, v68, v69
	ds_read_b128 v[68:71], v66 offset:64
	s_cmp_eq_u32 s18, 4
	s_waitcnt lgkmcnt(0)
	v_mul_f32_e32 v69, v69, v29
	v_fmac_f32_e32 v69, v68, v28
	v_fmac_f32_e32 v69, v70, v18
	v_fmac_f32_e32 v69, v71, v19
	v_add_f32_e32 v72, v72, v69
	ds_read_b128 v[68:71], v66 offset:80
	s_waitcnt lgkmcnt(0)
	v_mul_f32_e32 v69, v69, v27
	v_fmac_f32_e32 v69, v68, v26
	v_fmac_f32_e32 v69, v70, v13
	v_fmac_f32_e32 v69, v71, v12
	v_add_f32_e32 v72, v72, v69
	ds_read_b128 v[68:71], v66 offset:128
	s_waitcnt lgkmcnt(0)
	v_mul_f32_e32 v69, v69, v35
	v_fmac_f32_e32 v69, v68, v34
	v_fmac_f32_e32 v69, v70, v24
	v_fmac_f32_e32 v69, v71, v25
	v_add_f32_e32 v72, v72, v69
	ds_read_b128 v[68:71], v66 offset:144
	s_waitcnt lgkmcnt(0)
	v_mul_f32_e32 v69, v69, v33
	v_fmac_f32_e32 v69, v68, v32
	v_fmac_f32_e32 v69, v70, v11
	v_fmac_f32_e32 v69, v71, v10
	v_add_f32_e32 v72, v72, v69
	ds_read_b128 v[68:71], v66 offset:192
	s_waitcnt lgkmcnt(0)
	v_mul_f32_e32 v69, v69, v43
	v_fmac_f32_e32 v69, v68, v42
	v_fmac_f32_e32 v69, v70, v30
	v_fmac_f32_e32 v69, v71, v31
	v_add_f32_e32 v72, v72, v69
	ds_read_b128 v[68:71], v66 offset:208
	s_waitcnt lgkmcnt(0)
	v_mul_f32_e32 v69, v69, v41
	v_fmac_f32_e32 v69, v68, v40
	v_fmac_f32_e32 v69, v70, v9
	v_fmac_f32_e32 v69, v71, v8
	v_add_f32_e32 v72, v72, v69
	ds_read_b128 v[68:71], v66 offset:256
	s_waitcnt lgkmcnt(0)
	v_mul_f32_e32 v69, v69, v49
	v_fmac_f32_e32 v69, v68, v48
	v_fmac_f32_e32 v69, v70, v38
	v_fmac_f32_e32 v69, v71, v39
	v_add_f32_e32 v72, v72, v69
	ds_read_b128 v[68:71], v66 offset:272
	s_waitcnt lgkmcnt(0)
	v_mul_f32_e32 v69, v69, v47
	v_fmac_f32_e32 v69, v68, v46
	v_fmac_f32_e32 v69, v70, v7
	v_fmac_f32_e32 v69, v71, v6
	v_add_f32_e32 v72, v72, v69
	ds_read_b128 v[68:71], v66 offset:320
	s_waitcnt lgkmcnt(0)
	v_mul_f32_e32 v69, v69, v55
	v_fmac_f32_e32 v69, v68, v54
	v_fmac_f32_e32 v69, v70, v44
	v_fmac_f32_e32 v69, v71, v45
	v_add_f32_e32 v72, v72, v69
	ds_read_b128 v[68:71], v66 offset:336
	s_waitcnt lgkmcnt(0)
	v_mul_f32_e32 v69, v69, v53
	v_fmac_f32_e32 v69, v68, v52
	v_fmac_f32_e32 v69, v70, v5
	v_fmac_f32_e32 v69, v71, v4
	v_add_f32_e32 v72, v72, v69
	ds_read_b128 v[68:71], v66 offset:384
	s_waitcnt lgkmcnt(0)
	v_mul_f32_e32 v69, v69, v61
	v_fmac_f32_e32 v69, v68, v60
	v_fmac_f32_e32 v69, v70, v50
	v_fmac_f32_e32 v69, v71, v51
	v_add_f32_e32 v72, v72, v69
	ds_read_b128 v[68:71], v66 offset:400
	s_waitcnt lgkmcnt(0)
	v_mul_f32_e32 v69, v69, v59
	v_fmac_f32_e32 v69, v68, v58
	v_fmac_f32_e32 v69, v70, v3
	v_fmac_f32_e32 v69, v71, v2
	v_add_f32_e32 v72, v72, v69
	ds_read_b128 v[68:71], v66 offset:448
	s_waitcnt lgkmcnt(0)
	v_mul_f32_e32 v69, v69, v65
	v_fmac_f32_e32 v69, v68, v64
	v_fmac_f32_e32 v69, v70, v56
	v_fmac_f32_e32 v69, v71, v57
	v_add_f32_e32 v72, v72, v69
	ds_read_b128 v[68:71], v66 offset:464
	s_waitcnt lgkmcnt(0)
	v_mul_f32_e32 v69, v69, v63
	v_fmac_f32_e32 v69, v68, v62
	v_fmac_f32_e32 v69, v70, v1
	v_fmac_f32_e32 v69, v71, v0
	v_add_f32_e32 v68, v72, v69
	ds_read_b128 v[70:73], v66 offset:512
	ds_bpermute_b32 v69, v170, v68
	s_waitcnt lgkmcnt(1)
	v_mul_f32_e32 v71, v71, v23
	v_fmac_f32_e32 v71, v70, v22
	v_fmac_f32_e32 v71, v72, v16
	v_fmac_f32_e32 v71, v73, v17
	v_add_f32_e32 v74, 0, v71
	ds_read_b128 v[70:73], v66 offset:528
	s_waitcnt lgkmcnt(0)
	v_mul_f32_e32 v71, v71, v21
	v_fmac_f32_e32 v71, v70, v20
	v_fmac_f32_e32 v71, v72, v15
	v_fmac_f32_e32 v71, v73, v14
	v_add_f32_e32 v74, v74, v71
	ds_read_b128 v[70:73], v66 offset:576
	s_waitcnt lgkmcnt(0)
	v_mul_f32_e32 v71, v71, v29
	v_fmac_f32_e32 v71, v70, v28
	v_fmac_f32_e32 v71, v72, v18
	v_fmac_f32_e32 v71, v73, v19
	v_add_f32_e32 v74, v74, v71
	ds_read_b128 v[70:73], v66 offset:592
	s_waitcnt lgkmcnt(0)
	v_mul_f32_e32 v71, v71, v27
	v_fmac_f32_e32 v71, v70, v26
	v_fmac_f32_e32 v71, v72, v13
	v_fmac_f32_e32 v71, v73, v12
	v_add_f32_e32 v74, v74, v71
	ds_read_b128 v[70:73], v66 offset:640
	s_waitcnt lgkmcnt(0)
	v_mul_f32_e32 v71, v71, v35
	v_fmac_f32_e32 v71, v70, v34
	v_fmac_f32_e32 v71, v72, v24
	v_fmac_f32_e32 v71, v73, v25
	v_add_f32_e32 v74, v74, v71
	ds_read_b128 v[70:73], v66 offset:656
	s_waitcnt lgkmcnt(0)
	v_mul_f32_e32 v71, v71, v33
	v_fmac_f32_e32 v71, v70, v32
	v_fmac_f32_e32 v71, v72, v11
	v_fmac_f32_e32 v71, v73, v10
	v_add_f32_e32 v74, v74, v71
	ds_read_b128 v[70:73], v66 offset:704
	s_waitcnt lgkmcnt(0)
	v_mul_f32_e32 v71, v71, v43
	v_fmac_f32_e32 v71, v70, v42
	v_fmac_f32_e32 v71, v72, v30
	v_fmac_f32_e32 v71, v73, v31
	v_add_f32_e32 v74, v74, v71
	ds_read_b128 v[70:73], v66 offset:720
	s_waitcnt lgkmcnt(0)
	v_mul_f32_e32 v71, v71, v41
	v_fmac_f32_e32 v71, v70, v40
	v_fmac_f32_e32 v71, v72, v9
	v_fmac_f32_e32 v71, v73, v8
	v_add_f32_e32 v74, v74, v71
	ds_read_b128 v[70:73], v66 offset:768
	s_waitcnt lgkmcnt(0)
	v_mul_f32_e32 v71, v71, v49
	v_fmac_f32_e32 v71, v70, v48
	v_fmac_f32_e32 v71, v72, v38
	v_fmac_f32_e32 v71, v73, v39
	v_add_f32_e32 v74, v74, v71
	ds_read_b128 v[70:73], v66 offset:784
	s_waitcnt lgkmcnt(0)
	v_mul_f32_e32 v71, v71, v47
	v_fmac_f32_e32 v71, v70, v46
	v_fmac_f32_e32 v71, v72, v7
	v_fmac_f32_e32 v71, v73, v6
	v_add_f32_e32 v74, v74, v71
	ds_read_b128 v[70:73], v66 offset:832
	s_waitcnt lgkmcnt(0)
; #define LAS __attribute__((address_space(3)))
; __device__ __forceinline__ float bf2f(unsigned short v) { return __uint_as_float(((unsigned)v) << 16); }
; template <int DQK, bool MOBA>
; __device__ __forceinline__ void attn_unit(const Args& A, int b, int h, int qb, lptr lds) {
;     ...
;             for (int j = 0; j < 7; ++j) {
;                 float a = 0.f;
;                 if (j < own) {
; #pragma unroll
;                     for (int s = 0; s < NS; ++s) {
;                         const f32x4 k0 = *(const LAS f32x4*)(km + j * 128 + 16 * s + 8 * hi), k1 = *(const LAS f32x4*)(km + j * 128 + 16 * s + 8 * hi + 4);
;                         a += bf2f((unsigned short)qf[s][0]) * k0[0] + bf2f((unsigned short)qf[s][1]) * k0[1] + bf2f((unsigned short)qf[s][2]) * k0[2] + bf2f((unsigned short)qf[s][3]) * k0[3];
;                         a += bf2f((unsigned short)qf[s][4]) * k1[0] + bf2f((unsigned short)qf[s][5]) * k1[1] + bf2f((unsigned short)qf[s][6]) * k1[2] + bf2f((unsigned short)qf[s][7]) * k1[3];
;                     }
;                 }
;                 a += __shfl_xor(a, 32);
;                 g[j] = a;
	v_mul_f32_e32 v71, v71, v55
	v_fmac_f32_e32 v71, v70, v54
	v_fmac_f32_e32 v71, v72, v44
	v_fmac_f32_e32 v71, v73, v45
	v_add_f32_e32 v74, v74, v71
	ds_read_b128 v[70:73], v66 offset:848
	s_waitcnt lgkmcnt(0)
	v_mul_f32_e32 v71, v71, v53
	v_fmac_f32_e32 v71, v70, v52
	v_fmac_f32_e32 v71, v72, v5
	v_fmac_f32_e32 v71, v73, v4
	v_add_f32_e32 v74, v74, v71
	ds_read_b128 v[70:73], v66 offset:896
	s_waitcnt lgkmcnt(0)
	v_mul_f32_e32 v71, v71, v61
	v_fmac_f32_e32 v71, v70, v60
	v_fmac_f32_e32 v71, v72, v50
	v_fmac_f32_e32 v71, v73, v51
	v_add_f32_e32 v74, v74, v71
	ds_read_b128 v[70:73], v66 offset:912
	s_waitcnt lgkmcnt(0)
	v_mul_f32_e32 v71, v71, v59
	v_fmac_f32_e32 v71, v70, v58
	v_fmac_f32_e32 v71, v72, v3
	v_fmac_f32_e32 v71, v73, v2
	v_add_f32_e32 v74, v74, v71
	ds_read_b128 v[70:73], v66 offset:960
	s_waitcnt lgkmcnt(0)
	v_mul_f32_e32 v71, v71, v65
	v_fmac_f32_e32 v71, v70, v64
	v_fmac_f32_e32 v71, v72, v56
	v_fmac_f32_e32 v71, v73, v57
	v_add_f32_e32 v74, v74, v71
	ds_read_b128 v[70:73], v66 offset:976
	s_waitcnt lgkmcnt(0)
	v_mul_f32_e32 v71, v71, v63
	v_fmac_f32_e32 v71, v70, v62
	v_fmac_f32_e32 v71, v72, v1
	v_fmac_f32_e32 v71, v73, v0
	v_add_f32_e32 v70, v74, v71
	ds_read_b128 v[72:75], v66 offset:1024
	ds_bpermute_b32 v71, v170, v70
	s_waitcnt lgkmcnt(1)
	v_mul_f32_e32 v73, v73, v23
	v_fmac_f32_e32 v73, v72, v22
	v_fmac_f32_e32 v73, v74, v16
	v_fmac_f32_e32 v73, v75, v17
	v_add_f32_e32 v76, 0, v73
	ds_read_b128 v[72:75], v66 offset:1040
	s_waitcnt lgkmcnt(0)
	v_mul_f32_e32 v73, v73, v21
	v_fmac_f32_e32 v73, v72, v20
	v_fmac_f32_e32 v73, v74, v15
	v_fmac_f32_e32 v73, v75, v14
	v_add_f32_e32 v76, v76, v73
	ds_read_b128 v[72:75], v66 offset:1088
	s_waitcnt lgkmcnt(0)
	v_mul_f32_e32 v73, v73, v29
	v_fmac_f32_e32 v73, v72, v28
	v_fmac_f32_e32 v73, v74, v18
	v_fmac_f32_e32 v73, v75, v19
	v_add_f32_e32 v76, v76, v73
	ds_read_b128 v[72:75], v66 offset:1104
	s_waitcnt lgkmcnt(0)
	v_mul_f32_e32 v73, v73, v27
	v_fmac_f32_e32 v73, v72, v26
	v_fmac_f32_e32 v73, v74, v13
	v_fmac_f32_e32 v73, v75, v12
	v_add_f32_e32 v76, v76, v73
	ds_read_b128 v[72:75], v66 offset:1152
	s_waitcnt lgkmcnt(0)
	v_mul_f32_e32 v73, v73, v35
	v_fmac_f32_e32 v73, v72, v34
	v_fmac_f32_e32 v73, v74, v24
	v_fmac_f32_e32 v73, v75, v25
	v_add_f32_e32 v76, v76, v73
	ds_read_b128 v[72:75], v66 offset:1168
	s_waitcnt lgkmcnt(0)
	v_mul_f32_e32 v73, v73, v33
	v_fmac_f32_e32 v73, v72, v32
	v_fmac_f32_e32 v73, v74, v11
	v_fmac_f32_e32 v73, v75, v10
	v_add_f32_e32 v76, v76, v73
	ds_read_b128 v[72:75], v66 offset:1216
	s_waitcnt lgkmcnt(0)
	v_mul_f32_e32 v73, v73, v43
	v_fmac_f32_e32 v73, v72, v42
	v_fmac_f32_e32 v73, v74, v30
	v_fmac_f32_e32 v73, v75, v31
	v_add_f32_e32 v76, v76, v73
	ds_read_b128 v[72:75], v66 offset:1232
	s_waitcnt lgkmcnt(0)
	v_mul_f32_e32 v73, v73, v41
	v_fmac_f32_e32 v73, v72, v40
	v_fmac_f32_e32 v73, v74, v9
	v_fmac_f32_e32 v73, v75, v8
	v_add_f32_e32 v76, v76, v73
	ds_read_b128 v[72:75], v66 offset:1280
	s_waitcnt lgkmcnt(0)
	v_mul_f32_e32 v73, v73, v49
	v_fmac_f32_e32 v73, v72, v48
	v_fmac_f32_e32 v73, v74, v38
	v_fmac_f32_e32 v73, v75, v39
	v_add_f32_e32 v76, v76, v73
	ds_read_b128 v[72:75], v66 offset:1296
	s_waitcnt lgkmcnt(0)
	v_mul_f32_e32 v73, v73, v47
	v_fmac_f32_e32 v73, v72, v46
	v_fmac_f32_e32 v73, v74, v7
	v_fmac_f32_e32 v73, v75, v6
	v_add_f32_e32 v76, v76, v73
	ds_read_b128 v[72:75], v66 offset:1344
	s_waitcnt lgkmcnt(0)
	v_mul_f32_e32 v73, v73, v55
	v_fmac_f32_e32 v73, v72, v54
	v_fmac_f32_e32 v73, v74, v44
	v_fmac_f32_e32 v73, v75, v45
	v_add_f32_e32 v76, v76, v73
	ds_read_b128 v[72:75], v66 offset:1360
	s_waitcnt lgkmcnt(0)
	v_mul_f32_e32 v73, v73, v53
	v_fmac_f32_e32 v73, v72, v52
	v_fmac_f32_e32 v73, v74, v5
	v_fmac_f32_e32 v73, v75, v4
	v_add_f32_e32 v76, v76, v73
	ds_read_b128 v[72:75], v66 offset:1408
	s_waitcnt lgkmcnt(0)
	v_mul_f32_e32 v73, v73, v61
	v_fmac_f32_e32 v73, v72, v60
	v_fmac_f32_e32 v73, v74, v50
	v_fmac_f32_e32 v73, v75, v51
	v_add_f32_e32 v76, v76, v73
	ds_read_b128 v[72:75], v66 offset:1424
	s_waitcnt lgkmcnt(0)
	v_mul_f32_e32 v73, v73, v59
	v_fmac_f32_e32 v73, v72, v58
	v_fmac_f32_e32 v73, v74, v3
	v_fmac_f32_e32 v73, v75, v2
	v_add_f32_e32 v76, v76, v73
	ds_read_b128 v[72:75], v66 offset:1472
	s_waitcnt lgkmcnt(0)
	v_mul_f32_e32 v73, v73, v65
	v_fmac_f32_e32 v73, v72, v64
	v_fmac_f32_e32 v73, v74, v56
	v_fmac_f32_e32 v73, v75, v57
	v_add_f32_e32 v76, v76, v73
	ds_read_b128 v[72:75], v66 offset:1488
	s_waitcnt lgkmcnt(0)
	v_mul_f32_e32 v73, v73, v63
	v_fmac_f32_e32 v73, v72, v62
	v_fmac_f32_e32 v73, v74, v1
	v_fmac_f32_e32 v73, v75, v0
	v_add_f32_e32 v72, v76, v73
	ds_read_b128 v[74:77], v66 offset:1536
	ds_bpermute_b32 v73, v170, v72
	s_waitcnt lgkmcnt(1)
	v_mul_f32_e32 v75, v75, v23
	v_fmac_f32_e32 v75, v74, v22
	v_fmac_f32_e32 v75, v76, v16
	v_fmac_f32_e32 v75, v77, v17
	v_add_f32_e32 v78, 0, v75
	ds_read_b128 v[74:77], v66 offset:1552
	s_waitcnt lgkmcnt(0)
	v_mul_f32_e32 v75, v75, v21
	v_fmac_f32_e32 v75, v74, v20
	v_fmac_f32_e32 v75, v76, v15
	v_fmac_f32_e32 v75, v77, v14
	v_add_f32_e32 v78, v78, v75
	ds_read_b128 v[74:77], v66 offset:1600
	s_waitcnt lgkmcnt(0)
	v_mul_f32_e32 v75, v75, v29
	v_fmac_f32_e32 v75, v74, v28
	v_fmac_f32_e32 v75, v76, v18
	v_fmac_f32_e32 v75, v77, v19
	v_add_f32_e32 v78, v78, v75
	ds_read_b128 v[74:77], v66 offset:1616
	s_waitcnt lgkmcnt(0)
	v_mul_f32_e32 v75, v75, v27
	v_fmac_f32_e32 v75, v74, v26
	v_fmac_f32_e32 v75, v76, v13
	v_fmac_f32_e32 v75, v77, v12
	v_add_f32_e32 v78, v78, v75
	ds_read_b128 v[74:77], v66 offset:1664
	s_waitcnt lgkmcnt(0)
	v_mul_f32_e32 v75, v75, v35
	v_fmac_f32_e32 v75, v74, v34
	v_fmac_f32_e32 v75, v76, v24
	v_fmac_f32_e32 v75, v77, v25
	v_add_f32_e32 v78, v78, v75
	ds_read_b128 v[74:77], v66 offset:1680
	s_waitcnt lgkmcnt(0)
; #define LAS __attribute__((address_space(3)))
; __device__ __forceinline__ float bf2f(unsigned short v) { return __uint_as_float(((unsigned)v) << 16); }
; template <int DQK, bool MOBA>
; __device__ __forceinline__ void attn_unit(const Args& A, int b, int h, int qb, lptr lds) {
;     ...
;             for (int j = 0; j < 7; ++j) {
;                 float a = 0.f;
;                 if (j < own) {
; #pragma unroll
;                     for (int s = 0; s < NS; ++s) {
;                         const f32x4 k0 = *(const LAS f32x4*)(km + j * 128 + 16 * s + 8 * hi), k1 = *(const LAS f32x4*)(km + j * 128 + 16 * s + 8 * hi + 4);
;                         a += bf2f((unsigned short)qf[s][0]) * k0[0] + bf2f((unsigned short)qf[s][1]) * k0[1] + bf2f((unsigned short)qf[s][2]) * k0[2] + bf2f((unsigned short)qf[s][3]) * k0[3];
;                         a += bf2f((unsigned short)qf[s][4]) * k1[0] + bf2f((unsigned short)qf[s][5]) * k1[1] + bf2f((unsigned short)qf[s][6]) * k1[2] + bf2f((unsigned short)qf[s][7]) * k1[3];
;                     }
;                 }
;                 a += __shfl_xor(a, 32);
;                 g[j] = a;
	v_mul_f32_e32 v75, v75, v33
	v_fmac_f32_e32 v75, v74, v32
	v_fmac_f32_e32 v75, v76, v11
	v_fmac_f32_e32 v75, v77, v10
	v_add_f32_e32 v78, v78, v75
	ds_read_b128 v[74:77], v66 offset:1728
	s_waitcnt lgkmcnt(0)
	v_mul_f32_e32 v75, v75, v43
	v_fmac_f32_e32 v75, v74, v42
	v_fmac_f32_e32 v75, v76, v30
	v_fmac_f32_e32 v75, v77, v31
	v_add_f32_e32 v78, v78, v75
	ds_read_b128 v[74:77], v66 offset:1744
	s_waitcnt lgkmcnt(0)
	v_mul_f32_e32 v75, v75, v41
	v_fmac_f32_e32 v75, v74, v40
	v_fmac_f32_e32 v75, v76, v9
	v_fmac_f32_e32 v75, v77, v8
	v_add_f32_e32 v78, v78, v75
	ds_read_b128 v[74:77], v66 offset:1792
	s_waitcnt lgkmcnt(0)
	v_mul_f32_e32 v75, v75, v49
	v_fmac_f32_e32 v75, v74, v48
	v_fmac_f32_e32 v75, v76, v38
	v_fmac_f32_e32 v75, v77, v39
	v_add_f32_e32 v78, v78, v75
	ds_read_b128 v[74:77], v66 offset:1808
	s_waitcnt lgkmcnt(0)
	v_mul_f32_e32 v75, v75, v47
	v_fmac_f32_e32 v75, v74, v46
	v_fmac_f32_e32 v75, v76, v7
	v_fmac_f32_e32 v75, v77, v6
	v_add_f32_e32 v78, v78, v75
	ds_read_b128 v[74:77], v66 offset:1856
	s_waitcnt lgkmcnt(0)
	v_mul_f32_e32 v75, v75, v55
	v_fmac_f32_e32 v75, v74, v54
	v_fmac_f32_e32 v75, v76, v44
	v_fmac_f32_e32 v75, v77, v45
	v_add_f32_e32 v78, v78, v75
	ds_read_b128 v[74:77], v66 offset:1872
	s_waitcnt lgkmcnt(0)
	v_mul_f32_e32 v75, v75, v53
	v_fmac_f32_e32 v75, v74, v52
	v_fmac_f32_e32 v75, v76, v5
	v_fmac_f32_e32 v75, v77, v4
	v_add_f32_e32 v78, v78, v75
	ds_read_b128 v[74:77], v66 offset:1920
	s_waitcnt lgkmcnt(0)
	v_mul_f32_e32 v75, v75, v61
	v_fmac_f32_e32 v75, v74, v60
	v_fmac_f32_e32 v75, v76, v50
	v_fmac_f32_e32 v75, v77, v51
	v_add_f32_e32 v78, v78, v75
	ds_read_b128 v[74:77], v66 offset:1936
	s_waitcnt lgkmcnt(0)
	v_mul_f32_e32 v75, v75, v59
	v_fmac_f32_e32 v75, v74, v58
	v_fmac_f32_e32 v75, v76, v3
	v_fmac_f32_e32 v75, v77, v2
	v_add_f32_e32 v78, v78, v75
	ds_read_b128 v[74:77], v66 offset:1984
	s_waitcnt lgkmcnt(0)
	v_mul_f32_e32 v75, v75, v65
	v_fmac_f32_e32 v75, v74, v64
	v_fmac_f32_e32 v75, v76, v56
	v_fmac_f32_e32 v75, v77, v57
	v_add_f32_e32 v78, v78, v75
	ds_read_b128 v[74:77], v66 offset:2000
	s_waitcnt lgkmcnt(0)
	v_mul_f32_e32 v75, v75, v63
	v_fmac_f32_e32 v75, v74, v62
	v_fmac_f32_e32 v75, v76, v1
	v_fmac_f32_e32 v75, v77, v0
	v_add_f32_e32 v74, v78, v75
	ds_bpermute_b32 v75, v170, v74
	v_mov_b32_e32 v76, 0
	s_cbranch_scc1 .LBB0_764
; #define LAS __attribute__((address_space(3)))
; __device__ __forceinline__ float bf2f(unsigned short v) { return __uint_as_float(((unsigned)v) << 16); }
; template <int DQK, bool MOBA>
; __device__ __forceinline__ void attn_unit(const Args& A, int b, int h, int qb, lptr lds) {
;     ...
;             for (int j = 0; j < 7; ++j) {
;                 float a = 0.f;
;                 if (j < own) {
; #pragma unroll
;                     for (int s = 0; s < NS; ++s) {
;                         const f32x4 k0 = *(const LAS f32x4*)(km + j * 128 + 16 * s + 8 * hi), k1 = *(const LAS f32x4*)(km + j * 128 + 16 * s + 8 * hi + 4);
;                         a += bf2f((unsigned short)qf[s][0]) * k0[0] + bf2f((unsigned short)qf[s][1]) * k0[1] + bf2f((unsigned short)qf[s][2]) * k0[2] + bf2f((unsigned short)qf[s][3]) * k0[3];
;                         a += bf2f((unsigned short)qf[s][4]) * k1[0] + bf2f((unsigned short)qf[s][5]) * k1[1] + bf2f((unsigned short)qf[s][6]) * k1[2] + bf2f((unsigned short)qf[s][7]) * k1[3];
;                     }
;                 }
;                 a += __shfl_xor(a, 32);
;                 g[j] = a;
	ds_read_b128 v[76:79], v66 offset:2048
	ds_read_b128 v[90:93], v66 offset:2064
	v_mov_b32_e32 v96, v34
	v_mov_b32_e32 v97, v32
	s_waitcnt lgkmcnt(1)
	v_mul_f32_e32 v77, v77, v23
	v_fmac_f32_e32 v77, v76, v22
	v_fmac_f32_e32 v77, v78, v16
	v_fmac_f32_e32 v77, v79, v17
	v_add_f32_e32 v76, 0, v77
	s_waitcnt lgkmcnt(0)
	v_mul_f32_e32 v77, v91, v21
	v_fmac_f32_e32 v77, v90, v20
	v_fmac_f32_e32 v77, v92, v15
	v_fmac_f32_e32 v77, v93, v14
	v_add_f32_e32 v94, v76, v77
	ds_read_b128 v[76:79], v66 offset:2112
	ds_read_b128 v[90:93], v66 offset:2128
	s_waitcnt lgkmcnt(1)
	v_mul_f32_e32 v77, v77, v29
	v_fmac_f32_e32 v77, v76, v28
	v_fmac_f32_e32 v77, v78, v18
	v_fmac_f32_e32 v77, v79, v19
	v_add_f32_e32 v76, v94, v77
	s_waitcnt lgkmcnt(0)
	v_mul_f32_e32 v77, v91, v27
	v_fmac_f32_e32 v77, v90, v26
	v_fmac_f32_e32 v77, v92, v13
	v_fmac_f32_e32 v77, v93, v12
	v_add_f32_e32 v98, v76, v77
	ds_read_b128 v[76:79], v66 offset:2176
	ds_read_b128 v[90:93], v66 offset:2192
	s_waitcnt lgkmcnt(1)
	v_mov_b32_e32 v94, v76
	s_waitcnt lgkmcnt(0)
	v_mov_b32_e32 v95, v90
	v_mov_b32_e32 v90, v77
	v_mov_b32_e32 v76, v35
	v_mov_b32_e32 v77, v33
	v_pk_mul_f32 v[76:77], v[90:91], v[76:77]
	v_mov_b32_e32 v90, v78
	v_pk_fma_f32 v[76:77], v[94:95], v[96:97], v[76:77]
	v_mov_b32_e32 v91, v92
	v_mov_b32_e32 v94, v24
	v_mov_b32_e32 v95, v11
	v_pk_fma_f32 v[76:77], v[90:91], v[94:95], v[76:77]
	v_mov_b32_e32 v92, v79
	v_pk_mov_b32 v[78:79], v[24:25], v[10:11] op_sel:[1,0]
	v_mov_b32_e32 v96, v42
	v_pk_fma_f32 v[76:77], v[92:93], v[78:79], v[76:77]
	v_mov_b32_e32 v97, v40
	v_add_f32_e32 v76, v98, v76
	v_add_f32_e32 v98, v76, v77
	ds_read_b128 v[76:79], v66 offset:2240
	ds_read_b128 v[90:93], v66 offset:2256
	s_waitcnt lgkmcnt(1)
	v_mov_b32_e32 v94, v76
	s_waitcnt lgkmcnt(0)
	v_mov_b32_e32 v95, v90
	v_mov_b32_e32 v90, v77
	v_mov_b32_e32 v76, v43
	v_mov_b32_e32 v77, v41
	v_pk_mul_f32 v[76:77], v[90:91], v[76:77]
	v_mov_b32_e32 v90, v78
	v_pk_fma_f32 v[76:77], v[94:95], v[96:97], v[76:77]
	v_mov_b32_e32 v91, v92
	v_mov_b32_e32 v94, v30
	v_mov_b32_e32 v95, v9
	v_pk_fma_f32 v[76:77], v[90:91], v[94:95], v[76:77]
	v_mov_b32_e32 v92, v79
	v_pk_mov_b32 v[78:79], v[30:31], v[8:9] op_sel:[1,0]
	v_mov_b32_e32 v96, v48
	v_pk_fma_f32 v[76:77], v[92:93], v[78:79], v[76:77]
	v_mov_b32_e32 v97, v46
	v_add_f32_e32 v76, v98, v76
	v_add_f32_e32 v98, v76, v77
	ds_read_b128 v[76:79], v66 offset:2304
	ds_read_b128 v[90:93], v66 offset:2320
	s_waitcnt lgkmcnt(1)
	v_mov_b32_e32 v94, v76
	s_waitcnt lgkmcnt(0)
	v_mov_b32_e32 v95, v90
	v_mov_b32_e32 v90, v77
	v_mov_b32_e32 v76, v49
	v_mov_b32_e32 v77, v47
	v_pk_mul_f32 v[76:77], v[90:91], v[76:77]
	v_mov_b32_e32 v90, v78
	v_pk_fma_f32 v[76:77], v[94:95], v[96:97], v[76:77]
	v_mov_b32_e32 v91, v92
	v_mov_b32_e32 v94, v38
	v_mov_b32_e32 v95, v7
	v_pk_fma_f32 v[76:77], v[90:91], v[94:95], v[76:77]
	v_mov_b32_e32 v92, v79
	v_pk_mov_b32 v[78:79], v[38:39], v[6:7] op_sel:[1,0]
	v_mov_b32_e32 v96, v54
	v_pk_fma_f32 v[76:77], v[92:93], v[78:79], v[76:77]
	v_mov_b32_e32 v97, v52
	v_add_f32_e32 v76, v98, v76
	v_add_f32_e32 v98, v76, v77
	ds_read_b128 v[76:79], v66 offset:2368
	ds_read_b128 v[90:93], v66 offset:2384
	s_waitcnt lgkmcnt(1)
	v_mov_b32_e32 v94, v76
	s_waitcnt lgkmcnt(0)
	v_mov_b32_e32 v95, v90
	v_mov_b32_e32 v90, v77
	v_mov_b32_e32 v76, v55
	v_mov_b32_e32 v77, v53
	v_pk_mul_f32 v[76:77], v[90:91], v[76:77]
	v_mov_b32_e32 v90, v78
	v_pk_fma_f32 v[76:77], v[94:95], v[96:97], v[76:77]
	v_mov_b32_e32 v91, v92
	v_mov_b32_e32 v94, v44
	v_mov_b32_e32 v95, v5
	v_pk_fma_f32 v[76:77], v[90:91], v[94:95], v[76:77]
	v_mov_b32_e32 v92, v79
	v_pk_mov_b32 v[78:79], v[44:45], v[4:5] op_sel:[1,0]
	v_mov_b32_e32 v96, v60
	v_pk_fma_f32 v[76:77], v[92:93], v[78:79], v[76:77]
	v_mov_b32_e32 v97, v58
	v_add_f32_e32 v76, v98, v76
	v_add_f32_e32 v98, v76, v77
	ds_read_b128 v[76:79], v66 offset:2432
	ds_read_b128 v[90:93], v66 offset:2448
	s_waitcnt lgkmcnt(1)
	v_mov_b32_e32 v94, v76
	s_waitcnt lgkmcnt(0)
	v_mov_b32_e32 v95, v90
	v_mov_b32_e32 v90, v77
	v_mov_b32_e32 v76, v61
	v_mov_b32_e32 v77, v59
	v_pk_mul_f32 v[76:77], v[90:91], v[76:77]
	v_mov_b32_e32 v90, v78
	v_pk_fma_f32 v[76:77], v[94:95], v[96:97], v[76:77]
	v_mov_b32_e32 v91, v92
	v_mov_b32_e32 v94, v50
	v_mov_b32_e32 v95, v3
	v_pk_fma_f32 v[76:77], v[90:91], v[94:95], v[76:77]
	v_mov_b32_e32 v92, v79
	v_pk_mov_b32 v[78:79], v[50:51], v[2:3] op_sel:[1,0]
	v_mov_b32_e32 v96, v64
	v_pk_fma_f32 v[76:77], v[92:93], v[78:79], v[76:77]
	v_mov_b32_e32 v97, v62
	v_add_f32_e32 v76, v98, v76
	v_add_f32_e32 v98, v76, v77
	ds_read_b128 v[76:79], v66 offset:2496
	ds_read_b128 v[90:93], v66 offset:2512
	s_waitcnt lgkmcnt(1)
	v_mov_b32_e32 v94, v76
	s_waitcnt lgkmcnt(0)
	v_mov_b32_e32 v95, v90
	v_mov_b32_e32 v90, v77
	v_mov_b32_e32 v76, v65
	v_mov_b32_e32 v77, v63
	v_pk_mul_f32 v[76:77], v[90:91], v[76:77]
	v_mov_b32_e32 v90, v78
	v_pk_fma_f32 v[76:77], v[94:95], v[96:97], v[76:77]
	v_mov_b32_e32 v91, v92
	v_mov_b32_e32 v94, v56
	v_mov_b32_e32 v95, v1
	v_pk_fma_f32 v[76:77], v[90:91], v[94:95], v[76:77]
	v_mov_b32_e32 v92, v79
	v_pk_mov_b32 v[78:79], v[56:57], v[0:1] op_sel:[1,0]
	s_nop 0
	v_pk_fma_f32 v[76:77], v[92:93], v[78:79], v[76:77]
	s_nop 0
	v_add_f32_e32 v76, v98, v76
	v_add_f32_e32 v76, v76, v77

; __device__ __forceinline__ float bf2f(unsigned short v) { return __uint_as_float(((unsigned)v) << 16); }
; template <int DQK, bool MOBA>
; __device__ __forceinline__ void attn_unit(const Args& A, int b, int h, int qb, lptr lds) {
;     ...
;     int tid_o = threadIdx.x; asm volatile("" : "+v"(tid_o));
;     const int tid = tid_o, lane = tid & 63, r32 = lane & 31, hi = lane >> 5;
;     const int wid = __builtin_amdgcn_readfirstlane(tid >> 6);
;     const int tb = b * SEQ, q0 = qb * 256, own = qb, bh = b * NH + h;
;     const int qrow = tb + q0 + wid * 32 + r32;
;     const int qrel = wid * 32 + r32;
;     __syncthreads();
;     bf16x8 qf[NS];
;     {
;         const bf16* qp = A.Q + (size_t)qrow * A.q_pitch + h * DQK + 8 * hi;
; #pragma unroll
;         for (int s = 0; s < NS; ++s) qf[s] = *(const bf16x8*)(qp + 16 * s);
;     }
;     {
;         float ssn = 0.f;
; #pragma unroll
;         for (int s = 0; s < 8; ++s)
; #pragma unroll
;             for (int e = 0; e < 8; ++e) { const float f = bf2f((unsigned short)qf[s][e]); ssn += f * f; }
;         ssn += __shfl_xor(ssn, 32);
.LBB0_809:
	s_lshl_b32 s0, s21, 2
	s_add_i32 s0, s0, s19
	s_ashr_i32 s1, s0, 31
	s_lshr_b32 s1, s1, 29
	s_add_i32 s1, s0, s1
	v_mov_b32_e32 v106, v202
	s_and_b32 s4, s1, -8
	s_lshl_b32 s1, s1, 8
	v_readfirstlane_b32 s5, v106
	s_and_b32 s24, s1, 0xfffff800
	s_lshl_b32 s13, s22, 8
	s_ashr_i32 s15, s5, 1
	s_sub_i32 s0, s0, s4
	s_add_i32 s4, s13, s24
	s_and_b32 s23, s15, 0xffffffe0
	v_and_b32_e32 v108, 31, v106
	s_add_i32 s1, s23, s4
	v_or_b32_e32 v184, s1, v108
	v_mov_b32_e32 v214, 0x20000
	ds_read_b32 v216, v214 offset:80
	v_mov_b32_e32 v217, 0
	s_waitcnt lgkmcnt(0)
	v_lshl_add_u64 v[0:1], s[88:89], 0, v[216:217]
	v_mad_i64_i32 v[0:1], s[6:7], v184, s11, v[0:1]
	s_mul_i32 s6, s0, 0xc0
	v_bfe_u32 v107, v106, 5, 1
	s_ashr_i32 s7, s6, 31
	v_lshl_add_u64 v[0:1], s[6:7], 1, v[0:1]
	v_lshlrev_b32_e32 v180, 4, v107
	v_lshl_add_u64 v[82:83], v[0:1], 0, v[180:181]
	v_and_b32_e32 v76, 32, v106
	s_barrier
	global_load_dwordx4 v[84:87], v[82:83], off offset:224
	global_load_dwordx4 v[90:93], v[82:83], off offset:192
	global_load_dwordx4 v[98:101], v[82:83], off offset:160
	global_load_dwordx4 v[68:71], v[82:83], off offset:128
	global_load_dwordx4 v[60:63], v[82:83], off offset:96
	global_load_dwordx4 v[56:59], v[82:83], off offset:64
	global_load_dwordx4 v[48:51], v76, s[28:29] offset:16
	global_load_dwordx4 v[52:55], v76, s[28:29]
	global_load_dwordx4 v[40:43], v76, s[28:29] offset:80
	global_load_dwordx4 v[44:47], v76, s[28:29] offset:64
	global_load_dwordx4 v[32:35], v76, s[28:29] offset:144
	global_load_dwordx4 v[36:39], v76, s[28:29] offset:128
	global_load_dwordx4 v[24:27], v76, s[28:29] offset:208
	global_load_dwordx4 v[28:31], v76, s[28:29] offset:192
	global_load_dwordx4 v[64:67], v[82:83], off
	global_load_dwordx4 v[112:115], v[82:83], off offset:32
	global_load_dwordx4 v[16:19], v76, s[28:29] offset:272
	global_load_dwordx4 v[20:23], v76, s[28:29] offset:256
	global_load_dwordx4 v[8:11], v76, s[28:29] offset:336
	global_load_dwordx4 v[12:15], v76, s[28:29] offset:320
	v_and_b32_e32 v1, 64, v206
	v_xor_b32_e32 v0, 32, v206
	v_add_u32_e32 v109, 64, v1
	v_cmp_lt_i32_e32 vcc, v0, v109
	v_ashrrev_i32_e32 v185, 31, v184
	v_mov_b32_e32 v77, v181
	v_cndmask_b32_e32 v0, v206, v0, vcc
	v_lshlrev_b32_e32 v196, 2, v0
	global_load_dwordx4 v[0:3], v[82:83], off offset:256
	global_load_dwordx4 v[4:7], v[82:83], off offset:288
	v_and_b32_e32 v110, 63, v106
	s_lshl_b32 s25, s22, 2
	s_ashr_i32 s5, s4, 31
	s_add_i32 s26, s25, 4
	s_lshl_b64 s[44:45], s[4:5], 11
	s_add_u32 s1, s90, s44
	s_addc_u32 s5, s91, s45
	s_lshl_b32 s42, s0, 7
	s_ashr_i32 s43, s42, 31
	s_lshl_b64 s[6:7], s[42:43], 1
	s_add_u32 s0, s1, s6
	s_addc_u32 s1, s5, s7
	s_mov_b32 s5, 2
	s_mov_b32 s27, 0
	s_waitcnt vmcnt(21)
	v_and_b32_e32 v73, 0xffff0000, v87
	s_waitcnt vmcnt(7)
	v_and_b32_e32 v201, 0xffff0000, v64
	v_lshlrev_b32_e32 v200, 16, v64
	v_and_b32_e32 v195, 0xffff0000, v65
	v_lshlrev_b32_e32 v194, 16, v65
	v_pk_mul_f32 v[64:65], v[200:201], v[200:201]
	v_pk_mul_f32 v[198:199], v[194:195], v[194:195]
	v_add_f32_e32 v64, v64, v65
	v_and_b32_e32 v193, 0xffff0000, v66
	v_lshlrev_b32_e32 v192, 16, v66
	v_add_f32_e32 v64, v198, v64
	v_and_b32_e32 v189, 0xffff0000, v67
	v_lshlrev_b32_e32 v188, 16, v67
	v_pk_mul_f32 v[66:67], v[192:193], v[192:193]
	v_add_f32_e32 v64, v199, v64
	v_add_f32_e32 v64, v66, v64
	v_pk_mul_f32 v[190:191], v[188:189], v[188:189]
	v_add_f32_e32 v64, v67, v64
	s_waitcnt vmcnt(6)
	v_and_b32_e32 v187, 0xffff0000, v112
	v_lshlrev_b32_e32 v186, 16, v112
	v_add_f32_e32 v64, v190, v64
	v_and_b32_e32 v177, 0xffff0000, v113
	v_lshlrev_b32_e32 v176, 16, v113
	v_pk_mul_f32 v[112:113], v[186:187], v[186:187]
	v_add_f32_e32 v64, v191, v64
	v_add_f32_e32 v64, v112, v64
	v_pk_mul_f32 v[178:179], v[176:177], v[176:177]
	v_add_f32_e32 v64, v113, v64
	v_and_b32_e32 v175, 0xffff0000, v114
	v_lshlrev_b32_e32 v174, 16, v114
	v_add_f32_e32 v64, v178, v64
	v_and_b32_e32 v171, 0xffff0000, v115
	v_lshlrev_b32_e32 v170, 16, v115
	v_pk_mul_f32 v[114:115], v[174:175], v[174:175]
	v_add_f32_e32 v64, v179, v64
	v_add_f32_e32 v64, v114, v64
	v_pk_mul_f32 v[172:173], v[170:171], v[170:171]
	v_add_f32_e32 v64, v115, v64
	v_and_b32_e32 v169, 0xffff0000, v56
	v_lshlrev_b32_e32 v168, 16, v56
	v_add_f32_e32 v64, v172, v64
	v_and_b32_e32 v165, 0xffff0000, v57
	v_lshlrev_b32_e32 v164, 16, v57
	v_pk_mul_f32 v[56:57], v[168:169], v[168:169]
	v_add_f32_e32 v64, v173, v64
	v_add_f32_e32 v56, v56, v64
	v_pk_mul_f32 v[166:167], v[164:165], v[164:165]
	v_add_f32_e32 v56, v57, v56
	v_and_b32_e32 v163, 0xffff0000, v58
	v_lshlrev_b32_e32 v162, 16, v58
	v_add_f32_e32 v56, v166, v56
	v_and_b32_e32 v159, 0xffff0000, v59
	v_lshlrev_b32_e32 v158, 16, v59
	v_pk_mul_f32 v[58:59], v[162:163], v[162:163]
	v_add_f32_e32 v56, v167, v56
	v_add_f32_e32 v56, v58, v56
	v_pk_mul_f32 v[160:161], v[158:159], v[158:159]
	v_add_f32_e32 v56, v59, v56
	v_and_b32_e32 v157, 0xffff0000, v60
	v_lshlrev_b32_e32 v156, 16, v60
	v_add_f32_e32 v56, v160, v56
	v_and_b32_e32 v155, 0xffff0000, v61
	v_lshlrev_b32_e32 v154, 16, v61
	v_pk_mul_f32 v[60:61], v[156:157], v[156:157]
	v_add_f32_e32 v56, v161, v56
	v_add_f32_e32 v56, v60, v56
	v_pk_mul_f32 v[148:149], v[154:155], v[154:155]
	v_add_f32_e32 v56, v61, v56
	v_and_b32_e32 v153, 0xffff0000, v62
	v_lshlrev_b32_e32 v152, 16, v62
	v_add_f32_e32 v56, v148, v56
	v_and_b32_e32 v151, 0xffff0000, v63
	v_lshlrev_b32_e32 v150, 16, v63
	v_pk_mul_f32 v[62:63], v[152:153], v[152:153]
	v_add_f32_e32 v56, v149, v56
	v_add_f32_e32 v56, v62, v56
	v_pk_mul_f32 v[146:147], v[150:151], v[150:151]
	v_add_f32_e32 v56, v63, v56
	v_and_b32_e32 v105, 0xffff0000, v68
	v_lshlrev_b32_e32 v104, 16, v68
	v_add_f32_e32 v56, v146, v56
; __device__ __forceinline__ unsigned cvt_pk_bf16(float lo, float hi) { f32x2 v = {lo, hi}; bf16x2_t b = __builtin_convertvector(v, bf16x2_t); return __builtin_bit_cast(unsigned, b); }
; __device__ __forceinline__ float bf2f(unsigned short v) { return __uint_as_float(((unsigned)v) << 16); }
; template <int DQK, bool MOBA>
; __device__ __forceinline__ void attn_unit(const Args& A, int b, int h, int qb, lptr lds) {
;     ...
;         float ssn = 0.f;
; #pragma unroll
;         for (int s = 0; s < 8; ++s)
; #pragma unroll
;             for (int e = 0; e < 8; ++e) { const float f = bf2f((unsigned short)qf[s][e]); ssn += f * f; }
;         ssn += __shfl_xor(ssn, 32);
;         const float scn = __builtin_amdgcn_rsqf(ssn * (1.0f / 128.0f) + 1e-6f) * A.qscale;
; #pragma unroll
;         for (int s = 0; s < 8; ++s) {
;             const f32x4 g0 = *(const f32x4*)(A.gq_n + 16 * s + 8 * hi), g1 = *(const f32x4*)(A.gq_n + 16 * s + 8 * hi + 4);
;             u32x4 w;
;             w.x = cvt_pk_bf16(bf2f((unsigned short)qf[s][0]) * scn * g0[0], bf2f((unsigned short)qf[s][1]) * scn * g0[1]);
;             w.y = cvt_pk_bf16(bf2f((unsigned short)qf[s][2]) * scn * g0[2], bf2f((unsigned short)qf[s][3]) * scn * g0[3]);
;             w.z = cvt_pk_bf16(bf2f((unsigned short)qf[s][4]) * scn * g1[0], bf2f((unsigned short)qf[s][5]) * scn * g1[1]);
;             w.w = cvt_pk_bf16(bf2f((unsigned short)qf[s][6]) * scn * g1[2], bf2f((unsigned short)qf[s][7]) * scn * g1[3]);
;             qf[s] = __builtin_bit_cast(bf16x8, w);
;         }
	v_and_b32_e32 v103, 0xffff0000, v69
	v_lshlrev_b32_e32 v102, 16, v69
	v_pk_mul_f32 v[68:69], v[104:105], v[104:105]
	v_add_f32_e32 v56, v147, v56
	v_add_f32_e32 v56, v68, v56
	v_pk_mul_f32 v[144:145], v[102:103], v[102:103]
	v_add_f32_e32 v56, v69, v56
	v_lshlrev_b32_e32 v72, 16, v87
	v_and_b32_e32 v75, 0xffff0000, v86
	v_lshlrev_b32_e32 v74, 16, v86
	v_and_b32_e32 v79, 0xffff0000, v85
	v_lshlrev_b32_e32 v78, 16, v85
	v_and_b32_e32 v81, 0xffff0000, v84
	v_lshlrev_b32_e32 v80, 16, v84
	v_and_b32_e32 v85, 0xffff0000, v93
	v_lshlrev_b32_e32 v84, 16, v93
	v_and_b32_e32 v87, 0xffff0000, v92
	v_lshlrev_b32_e32 v86, 16, v92
	v_and_b32_e32 v93, 0xffff0000, v101
	v_lshlrev_b32_e32 v92, 16, v101
	v_and_b32_e32 v95, 0xffff0000, v100
	v_lshlrev_b32_e32 v94, 16, v100
	v_and_b32_e32 v101, 0xffff0000, v71
	v_lshlrev_b32_e32 v100, 16, v71
	v_and_b32_e32 v71, 0xffff0000, v70
	v_lshlrev_b32_e32 v70, 16, v70
	v_add_f32_e32 v56, v144, v56
	v_pk_mul_f32 v[142:143], v[70:71], v[70:71]
	v_add_f32_e32 v56, v145, v56
	v_add_f32_e32 v56, v142, v56
	v_pk_mul_f32 v[140:141], v[100:101], v[100:101]
	v_add_f32_e32 v56, v143, v56
	v_and_b32_e32 v97, 0xffff0000, v99
	v_lshlrev_b32_e32 v96, 16, v99
	v_and_b32_e32 v99, 0xffff0000, v98
	v_lshlrev_b32_e32 v98, 16, v98
	v_add_f32_e32 v56, v140, v56
	v_pk_mul_f32 v[138:139], v[98:99], v[98:99]
	v_add_f32_e32 v56, v141, v56
	v_add_f32_e32 v56, v138, v56
	v_pk_mul_f32 v[136:137], v[96:97], v[96:97]
	v_add_f32_e32 v56, v139, v56
	v_add_f32_e32 v56, v136, v56
	v_pk_mul_f32 v[134:135], v[94:95], v[94:95]
	v_add_f32_e32 v56, v137, v56
	v_add_f32_e32 v56, v134, v56
	v_pk_mul_f32 v[132:133], v[92:93], v[92:93]
	v_add_f32_e32 v56, v135, v56
	v_and_b32_e32 v89, 0xffff0000, v91
	v_lshlrev_b32_e32 v88, 16, v91
	v_and_b32_e32 v91, 0xffff0000, v90
	v_lshlrev_b32_e32 v90, 16, v90
	v_add_f32_e32 v56, v132, v56
	v_pk_mul_f32 v[130:131], v[90:91], v[90:91]
	v_add_f32_e32 v56, v133, v56
	v_add_f32_e32 v56, v130, v56
	v_pk_mul_f32 v[128:129], v[88:89], v[88:89]
	v_add_f32_e32 v56, v131, v56
	v_add_f32_e32 v56, v128, v56
	v_pk_mul_f32 v[126:127], v[86:87], v[86:87]
	v_add_f32_e32 v56, v129, v56
	v_add_f32_e32 v56, v126, v56
	v_pk_mul_f32 v[124:125], v[84:85], v[84:85]
	v_add_f32_e32 v56, v127, v56
	v_add_f32_e32 v56, v124, v56
	v_pk_mul_f32 v[122:123], v[80:81], v[80:81]
	v_add_f32_e32 v56, v125, v56
	v_add_f32_e32 v56, v122, v56
	v_pk_mul_f32 v[120:121], v[78:79], v[78:79]
	v_add_f32_e32 v56, v123, v56
	v_add_f32_e32 v56, v120, v56
	v_pk_mul_f32 v[118:119], v[74:75], v[74:75]
	v_add_f32_e32 v56, v121, v56
	v_add_f32_e32 v56, v118, v56
	v_pk_mul_f32 v[116:117], v[72:73], v[72:73]
	v_add_f32_e32 v56, v119, v56
	v_add_f32_e32 v56, v116, v56
	v_add_f32_e32 v56, v117, v56
	global_load_dwordx4 v[60:63], v[82:83], off offset:320
	global_load_dwordx4 v[64:67], v[82:83], off offset:352
	global_load_dwordx4 v[138:141], v76, s[28:29] offset:400
	global_load_dwordx4 v[142:145], v76, s[28:29] offset:384
	ds_bpermute_b32 v57, v196, v56
	v_ashrrev_i32_e32 v199, 3, v106
	s_waitcnt lgkmcnt(0)
	v_add_f32_e32 v56, v56, v57
	v_fmamk_f32 v56, v56, 0x3c000000, v204
	v_rsq_f32_e32 v68, v56
	global_load_dwordx4 v[56:59], v76, s[28:29] offset:464
	global_load_dwordx4 v[146:149], v76, s[28:29] offset:448
	v_mul_f32_e32 v68, 0x3dd53b94, v68
	v_pk_mul_f32 v[82:83], v[68:69], v[200:201] op_sel_hi:[0,1]
	v_pk_mul_f32 v[52:53], v[52:53], v[82:83]
	s_nop 0
	v_cvt_pk_bf16_f32 v112, v52, v53
	v_pk_mul_f32 v[52:53], v[68:69], v[194:195] op_sel_hi:[0,1]
	v_pk_mul_f32 v[52:53], v[54:55], v[52:53]
	s_nop 0
	v_cvt_pk_bf16_f32 v113, v52, v53
	v_pk_mul_f32 v[52:53], v[68:69], v[192:193] op_sel_hi:[0,1]
	v_pk_mul_f32 v[48:49], v[48:49], v[52:53]
	s_nop 0
	v_cvt_pk_bf16_f32 v114, v48, v49
	v_pk_mul_f32 v[48:49], v[68:69], v[188:189] op_sel_hi:[0,1]
	v_pk_mul_f32 v[48:49], v[50:51], v[48:49]
	v_mov_b32_e32 v189, v181
	v_cvt_pk_bf16_f32 v115, v48, v49
	v_pk_mul_f32 v[48:49], v[68:69], v[186:187] op_sel_hi:[0,1]
	v_pk_mul_f32 v[44:45], v[44:45], v[48:49]
	v_mov_b32_e32 v187, v181
	v_cvt_pk_bf16_f32 v116, v44, v45
	v_pk_mul_f32 v[44:45], v[68:69], v[176:177] op_sel_hi:[0,1]
	v_pk_mul_f32 v[44:45], v[46:47], v[44:45]
	s_nop 0
	v_cvt_pk_bf16_f32 v117, v44, v45
	v_pk_mul_f32 v[44:45], v[68:69], v[174:175] op_sel_hi:[0,1]
	v_pk_mul_f32 v[40:41], v[40:41], v[44:45]
	s_nop 0
	v_cvt_pk_bf16_f32 v118, v40, v41
	v_pk_mul_f32 v[40:41], v[68:69], v[170:171] op_sel_hi:[0,1]
	v_pk_mul_f32 v[40:41], v[42:43], v[40:41]
	s_nop 0
	v_cvt_pk_bf16_f32 v119, v40, v41
	v_pk_mul_f32 v[40:41], v[68:69], v[168:169] op_sel_hi:[0,1]
	v_pk_mul_f32 v[36:37], v[36:37], v[40:41]
	s_waitcnt vmcnt(5)
; __device__ __forceinline__ unsigned cvt_pk_bf16(float lo, float hi) { f32x2 v = {lo, hi}; bf16x2_t b = __builtin_convertvector(v, bf16x2_t); return __builtin_bit_cast(unsigned, b); }
; __device__ __forceinline__ float bf2f(unsigned short v) { return __uint_as_float(((unsigned)v) << 16); }
; template <int DQK, bool MOBA>
; __device__ __forceinline__ void attn_unit(const Args& A, int b, int h, int qb, lptr lds) {
;     ...
; #pragma unroll
;         for (int s = 0; s < 8; ++s) {
;             const f32x4 g0 = *(const f32x4*)(A.gq_n + 16 * s + 8 * hi), g1 = *(const f32x4*)(A.gq_n + 16 * s + 8 * hi + 4);
;             u32x4 w;
;             w.x = cvt_pk_bf16(bf2f((unsigned short)qf[s][0]) * scn * g0[0], bf2f((unsigned short)qf[s][1]) * scn * g0[1]);
;             w.y = cvt_pk_bf16(bf2f((unsigned short)qf[s][2]) * scn * g0[2], bf2f((unsigned short)qf[s][3]) * scn * g0[3]);
;             w.z = cvt_pk_bf16(bf2f((unsigned short)qf[s][4]) * scn * g1[0], bf2f((unsigned short)qf[s][5]) * scn * g1[1]);
;             w.w = cvt_pk_bf16(bf2f((unsigned short)qf[s][6]) * scn * g1[2], bf2f((unsigned short)qf[s][7]) * scn * g1[3]);
;             qf[s] = __builtin_bit_cast(bf16x8, w);
;         }
;         if (DQK == 192) {
;             float ssr = 0.f;
; #pragma unroll
;             for (int s = 8; s < NS; ++s)
; #pragma unroll
;                 for (int e = 0; e < 8; ++e) { const float f = bf2f((unsigned short)qf[s][e]); ssr += f * f; }
;             ssr += __shfl_xor(ssr, 32);
;             const float scr = __builtin_amdgcn_rsqf(ssr * (1.0f / 64.0f) + 1e-6f);
; #pragma unroll
;             for (int sp = 0; sp < 2; ++sp) {
;                 const int i0 = 16 * sp + 8 * hi;
;                 float o1[8], o2[8];
;                 const f32x4 ga0 = *(const f32x4*)(A.gq_r + i0), ga1 = *(const f32x4*)(A.gq_r + i0 + 4), gb0 = *(const f32x4*)(A.gq_r + 32 + i0), gb1 = *(const f32x4*)(A.gq_r + 32 + i0 + 4);
;                 const f32x4 cc0 = *(const f32x4*)(A.cosT + (size_t)qrow * 32 + i0), cc1 = *(const f32x4*)(A.cosT + (size_t)qrow * 32 + i0 + 4);
;                 const f32x4 ss0 = *(const f32x4*)(A.sinT + (size_t)qrow * 32 + i0), ss1 = *(const f32x4*)(A.sinT + (size_t)qrow * 32 + i0 + 4);
	v_and_b32_e32 v169, 0xffff0000, v61
	v_cvt_pk_bf16_f32 v120, v36, v37
	v_pk_mul_f32 v[36:37], v[68:69], v[164:165] op_sel_hi:[0,1]
	v_pk_mul_f32 v[36:37], v[38:39], v[36:37]
	v_and_b32_e32 v165, 0xffff0000, v1
	v_cvt_pk_bf16_f32 v121, v36, v37
	v_pk_mul_f32 v[36:37], v[68:69], v[162:163] op_sel_hi:[0,1]
	v_pk_mul_f32 v[32:33], v[32:33], v[36:37]
	v_lshlrev_b32_e32 v164, 16, v1
	v_cvt_pk_bf16_f32 v122, v32, v33
	v_pk_mul_f32 v[32:33], v[68:69], v[158:159] op_sel_hi:[0,1]
	v_pk_mul_f32 v[32:33], v[34:35], v[32:33]
	v_and_b32_e32 v1, 0xffff0000, v0
	v_cvt_pk_bf16_f32 v123, v32, v33
	v_pk_mul_f32 v[32:33], v[68:69], v[156:157] op_sel_hi:[0,1]
	v_pk_mul_f32 v[28:29], v[28:29], v[32:33]
	v_lshlrev_b32_e32 v0, 16, v0
	v_cvt_pk_bf16_f32 v124, v28, v29
	v_pk_mul_f32 v[28:29], v[68:69], v[154:155] op_sel_hi:[0,1]
	v_pk_mul_f32 v[28:29], v[30:31], v[28:29]
	v_pk_mul_f32 v[172:173], v[0:1], v[0:1]
	v_cvt_pk_bf16_f32 v125, v28, v29
	v_pk_mul_f32 v[28:29], v[68:69], v[152:153] op_sel_hi:[0,1]
	v_pk_mul_f32 v[24:25], v[24:25], v[28:29]
	global_load_dwordx4 v[28:31], v76, s[30:31] offset:16
	global_load_dwordx4 v[32:35], v76, s[30:31]
	global_load_dwordx4 v[36:39], v76, s[30:31] offset:144
	global_load_dwordx4 v[40:43], v76, s[30:31] offset:128
	v_cvt_pk_bf16_f32 v126, v24, v25
	v_pk_mul_f32 v[24:25], v[68:69], v[150:151] op_sel_hi:[0,1]
	v_pk_mul_f32 v[24:25], v[26:27], v[24:25]
	v_pk_mul_f32 v[166:167], v[164:165], v[164:165]
	v_cvt_pk_bf16_f32 v127, v24, v25
	v_pk_mul_f32 v[24:25], v[68:69], v[104:105] op_sel_hi:[0,1]
	v_pk_mul_f32 v[20:21], v[20:21], v[24:25]
	v_and_b32_e32 v151, 0xffff0000, v3
	v_cvt_pk_bf16_f32 v128, v20, v21
	v_pk_mul_f32 v[20:21], v[68:69], v[102:103] op_sel_hi:[0,1]
	v_pk_mul_f32 v[20:21], v[22:23], v[20:21]
	v_lshlrev_b32_e32 v150, 16, v3
	v_cvt_pk_bf16_f32 v129, v20, v21
	v_pk_mul_f32 v[20:21], v[68:69], v[70:71] op_sel_hi:[0,1]
	v_pk_mul_f32 v[16:17], v[16:17], v[20:21]
	v_and_b32_e32 v3, 0xffff0000, v2
	v_cvt_pk_bf16_f32 v130, v16, v17
	v_pk_mul_f32 v[16:17], v[68:69], v[100:101] op_sel_hi:[0,1]
	v_pk_mul_f32 v[16:17], v[18:19], v[16:17]
	v_lshlrev_b32_e32 v2, 16, v2
	v_cvt_pk_bf16_f32 v131, v16, v17
	v_pk_mul_f32 v[16:17], v[68:69], v[98:99] op_sel_hi:[0,1]
	v_pk_mul_f32 v[12:13], v[12:13], v[16:17]
	v_pk_mul_f32 v[160:161], v[2:3], v[2:3]
	v_cvt_pk_bf16_f32 v132, v12, v13
	v_pk_mul_f32 v[12:13], v[68:69], v[96:97] op_sel_hi:[0,1]
	v_pk_mul_f32 v[12:13], v[14:15], v[12:13]
	v_pk_mul_f32 v[154:155], v[150:151], v[150:151]
	v_cvt_pk_bf16_f32 v133, v12, v13
	v_pk_mul_f32 v[12:13], v[68:69], v[94:95] op_sel_hi:[0,1]
	v_pk_mul_f32 v[8:9], v[8:9], v[12:13]
	v_and_b32_e32 v105, 0xffff0000, v5
	v_cvt_pk_bf16_f32 v134, v8, v9
	v_pk_mul_f32 v[8:9], v[68:69], v[92:93] op_sel_hi:[0,1]
	v_pk_mul_f32 v[8:9], v[10:11], v[8:9]
	v_lshlrev_b32_e32 v104, 16, v5
	v_cvt_pk_bf16_f32 v135, v8, v9
	v_pk_mul_f32 v[8:9], v[68:69], v[90:91] op_sel_hi:[0,1]
	s_waitcnt vmcnt(6)
	v_pk_mul_f32 v[8:9], v[142:143], v[8:9]
	v_and_b32_e32 v5, 0xffff0000, v4
	v_cvt_pk_bf16_f32 v136, v8, v9
	v_pk_mul_f32 v[8:9], v[68:69], v[88:89] op_sel_hi:[0,1]
	v_pk_mul_f32 v[8:9], v[144:145], v[8:9]
	v_lshlrev_b32_e32 v4, 16, v4
	v_cvt_pk_bf16_f32 v137, v8, v9
	v_pk_mul_f32 v[8:9], v[68:69], v[86:87] op_sel_hi:[0,1]
	v_pk_mul_f32 v[8:9], v[138:139], v[8:9]
	v_pk_mul_f32 v[142:143], v[104:105], v[104:105]
	v_cvt_pk_bf16_f32 v138, v8, v9
	v_pk_mul_f32 v[8:9], v[68:69], v[84:85] op_sel_hi:[0,1]
	v_pk_mul_f32 v[8:9], v[140:141], v[8:9]
	v_lshlrev_b32_e32 v168, 16, v61
	v_cvt_pk_bf16_f32 v139, v8, v9
	v_pk_mul_f32 v[8:9], v[68:69], v[80:81] op_sel_hi:[0,1]
	s_waitcnt vmcnt(4)
	v_pk_mul_f32 v[8:9], v[146:147], v[8:9]
	v_pk_mul_f32 v[146:147], v[4:5], v[4:5]
	v_cvt_pk_bf16_f32 v140, v8, v9
	v_pk_mul_f32 v[8:9], v[68:69], v[78:79] op_sel_hi:[0,1]
	v_pk_mul_f32 v[70:71], v[148:149], v[8:9]
	v_lshlrev_b64 v[8:9], 7, v[184:185]
	v_lshl_add_u64 v[10:11], s[76:77], 0, v[8:9]
	v_lshl_add_u64 v[12:13], v[10:11], 0, v[76:77]
	global_load_dwordx4 v[44:47], v[12:13], off offset:16
	global_load_dwordx4 v[48:51], v[12:13], off
	v_lshl_add_u64 v[8:9], s[78:79], 0, v[8:9]
	v_lshl_add_u64 v[24:25], v[8:9], 0, v[76:77]
	global_load_dwordx4 v[52:55], v[24:25], off offset:16
	global_load_dwordx4 v[78:81], v[24:25], off
	global_load_dwordx4 v[20:23], v76, s[30:31] offset:80
	global_load_dwordx4 v[82:85], v76, s[30:31] offset:64
	global_load_dwordx4 v[16:19], v76, s[30:31] offset:208
	global_load_dwordx4 v[86:89], v76, s[30:31] offset:192
	global_load_dwordx4 v[8:11], v[12:13], off offset:80
	global_load_dwordx4 v[90:93], v[12:13], off offset:64
	s_nop 0
	global_load_dwordx4 v[12:15], v[24:25], off offset:80
	global_load_dwordx4 v[94:97], v[24:25], off offset:64
	v_add_f32_e32 v69, v172, v173
	v_add_f32_e32 v69, v166, v69
	v_add_f32_e32 v69, v167, v69
	v_add_f32_e32 v69, v160, v69
	v_add_f32_e32 v69, v161, v69
	v_add_f32_e32 v69, v154, v69
	v_add_f32_e32 v69, v155, v69
	v_add_f32_e32 v69, v146, v69
	v_add_f32_e32 v69, v147, v69
	v_and_b32_e32 v25, 0xffff0000, v7
	v_lshlrev_b32_e32 v24, 16, v7
	v_and_b32_e32 v7, 0xffff0000, v6
	v_lshlrev_b32_e32 v6, 16, v6
	v_add_f32_e32 v69, v142, v69
	v_pk_mul_f32 v[100:101], v[6:7], v[6:7]
	v_add_f32_e32 v69, v143, v69
	v_add_f32_e32 v69, v100, v69
	v_pk_mul_f32 v[76:77], v[24:25], v[24:25]
	v_add_f32_e32 v69, v101, v69
	v_and_b32_e32 v61, 0xffff0000, v60
	v_lshlrev_b32_e32 v60, 16, v60
	v_add_f32_e32 v69, v76, v69
	v_pk_mul_f32 v[174:175], v[60:61], v[60:61]
	v_add_f32_e32 v69, v77, v69
	v_add_f32_e32 v69, v174, v69
	v_pk_mul_f32 v[170:171], v[168:169], v[168:169]
	v_add_f32_e32 v69, v175, v69
	v_and_b32_e32 v157, 0xffff0000, v63
	v_lshlrev_b32_e32 v156, 16, v63
	v_and_b32_e32 v63, 0xffff0000, v62
	v_lshlrev_b32_e32 v62, 16, v62
	v_add_f32_e32 v69, v170, v69
	v_pk_mul_f32 v[162:163], v[62:63], v[62:63]
	v_add_f32_e32 v69, v171, v69
	v_add_f32_e32 v69, v162, v69
	v_pk_mul_f32 v[158:159], v[156:157], v[156:157]
	v_add_f32_e32 v69, v163, v69
	v_and_b32_e32 v153, 0xffff0000, v65
	v_lshlrev_b32_e32 v152, 16, v65
	v_and_b32_e32 v65, 0xffff0000, v64
	v_lshlrev_b32_e32 v64, 16, v64
	v_add_f32_e32 v69, v158, v69
	v_pk_mul_f32 v[148:149], v[64:65], v[64:65]
	v_add_f32_e32 v69, v159, v69
	v_add_f32_e32 v69, v148, v69
	v_pk_mul_f32 v[144:145], v[152:153], v[152:153]
	v_add_f32_e32 v69, v149, v69
	v_and_b32_e32 v27, 0xffff0000, v67
	v_lshlrev_b32_e32 v26, 16, v67
	v_and_b32_e32 v67, 0xffff0000, v66
	v_lshlrev_b32_e32 v66, 16, v66
	v_add_f32_e32 v69, v144, v69
	v_pk_mul_f32 v[102:103], v[66:67], v[66:67]
	v_add_f32_e32 v69, v145, v69
	v_add_f32_e32 v69, v102, v69
	v_pk_mul_f32 v[98:99], v[26:27], v[26:27]
	v_add_f32_e32 v69, v103, v69
	v_add_f32_e32 v69, v98, v69
	v_add_f32_e32 v69, v99, v69
	ds_bpermute_b32 v76, v196, v69
	v_cvt_pk_bf16_f32 v141, v70, v71
	v_pk_mul_f32 v[70:71], v[68:69], v[74:75] op_sel_hi:[0,1]
	v_pk_mul_f32 v[56:57], v[56:57], v[70:71]
	s_nop 0
	v_cvt_pk_bf16_f32 v142, v56, v57
	s_waitcnt lgkmcnt(0)
; __device__ __forceinline__ unsigned cvt_pk_bf16(float lo, float hi) { f32x2 v = {lo, hi}; bf16x2_t b = __builtin_convertvector(v, bf16x2_t); return __builtin_bit_cast(unsigned, b); }
; __device__ __forceinline__ float bf2f(unsigned short v) { return __uint_as_float(((unsigned)v) << 16); }
; template <int DQK, bool MOBA>
; __device__ __forceinline__ void attn_unit(const Args& A, int b, int h, int qb, lptr lds) {
;     ...
;             const float scr = __builtin_amdgcn_rsqf(ssr * (1.0f / 64.0f) + 1e-6f);
; #pragma unroll
;             for (int sp = 0; sp < 2; ++sp) {
;                 const int i0 = 16 * sp + 8 * hi;
;                 float o1[8], o2[8];
;                 const f32x4 ga0 = *(const f32x4*)(A.gq_r + i0), ga1 = *(const f32x4*)(A.gq_r + i0 + 4), gb0 = *(const f32x4*)(A.gq_r + 32 + i0), gb1 = *(const f32x4*)(A.gq_r + 32 + i0 + 4);
;                 const f32x4 cc0 = *(const f32x4*)(A.cosT + (size_t)qrow * 32 + i0), cc1 = *(const f32x4*)(A.cosT + (size_t)qrow * 32 + i0 + 4);
;                 const f32x4 ss0 = *(const f32x4*)(A.sinT + (size_t)qrow * 32 + i0), ss1 = *(const f32x4*)(A.sinT + (size_t)qrow * 32 + i0 + 4);
; #pragma unroll
;                 for (int e = 0; e < 8; ++e) {
;                     const float x1 = bf2f((unsigned short)qf[(NS == 12 ? 8 : 0) + sp][e]) * scr * (e < 4 ? ga0[e & 3] : ga1[e & 3]);
;                     const float x2 = bf2f((unsigned short)qf[(NS == 12 ? 10 : 0) + sp][e]) * scr * (e < 4 ? gb0[e & 3] : gb1[e & 3]);
;                     const float c = e < 4 ? cc0[e & 3] : cc1[e & 3], sn = e < 4 ? ss0[e & 3] : ss1[e & 3];
;                     o1[e] = (x1 * c - x2 * sn) * A.qscale; o2[e] = (x2 * c + x1 * sn) * A.qscale;
;                 }
;                 u32x4 w1, w2;
;                 w1.x = cvt_pk_bf16(o1[0], o1[1]); w1.y = cvt_pk_bf16(o1[2], o1[3]); w1.z = cvt_pk_bf16(o1[4], o1[5]); w1.w = cvt_pk_bf16(o1[6], o1[7]);
;                 w2.x = cvt_pk_bf16(o2[0], o2[1]); w2.y = cvt_pk_bf16(o2[2], o2[3]); w2.z = cvt_pk_bf16(o2[4], o2[5]); w2.w = cvt_pk_bf16(o2[6], o2[7]);
;                 qf[(NS == 12 ? 8 : 0) + sp] = __builtin_bit_cast(bf16x8, w1); qf[(NS == 12 ? 10 : 0) + sp] = __builtin_bit_cast(bf16x8, w2);
;     ...
;         float qss = 0.f;
; #pragma unroll
;         for (int s = 0; s < NS; ++s)
; #pragma unroll
;             for (int e = 0; e < 8; ++e) { const float f = bf2f((unsigned short)qf[s][e]); qss += f * f; }
	v_add_f32_e32 v56, v69, v76
	v_fmamk_f32 v56, v56, 0x3c800000, v204
	v_rsq_f32_e32 v56, v56
	v_pk_mul_f32 v[68:69], v[68:69], v[72:73] op_sel_hi:[0,1]
	v_pk_mul_f32 v[58:59], v[58:59], v[68:69]
	v_pk_mul_f32 v[0:1], v[56:57], v[0:1] op_sel_hi:[0,1]
	s_waitcnt vmcnt(14)
	v_pk_mul_f32 v[0:1], v[32:33], v[0:1]
	v_pk_mul_f32 v[32:33], v[56:57], v[60:61] op_sel_hi:[0,1]
	s_waitcnt vmcnt(12)
	v_pk_mul_f32 v[32:33], v[40:41], v[32:33]
	v_pk_mul_f32 v[2:3], v[56:57], v[2:3] op_sel_hi:[0,1]
	s_waitcnt vmcnt(8)
	v_pk_mul_f32 v[40:41], v[78:79], v[32:33]
	v_pk_mul_f32 v[2:3], v[28:29], v[2:3]
	v_pk_fma_f32 v[40:41], v[48:49], v[0:1], v[40:41] neg_lo:[0,0,1] neg_hi:[0,0,1]
	v_pk_mul_f32 v[0:1], v[78:79], v[0:1]
	v_pk_mul_f32 v[28:29], v[56:57], v[62:63] op_sel_hi:[0,1]
	v_pk_fma_f32 v[0:1], v[48:49], v[32:33], v[0:1]
	v_pk_mul_f32 v[32:33], v[56:57], v[164:165] op_sel_hi:[0,1]
	v_pk_mul_f32 v[32:33], v[34:35], v[32:33]
	v_pk_mul_f32 v[34:35], v[56:57], v[168:169] op_sel_hi:[0,1]
	v_pk_mul_f32 v[34:35], v[42:43], v[34:35]
	v_pk_mul_f32 v[28:29], v[36:37], v[28:29]
	v_pk_mul_f32 v[42:43], v[80:81], v[34:35]
	v_pk_mul_f32 v[0:1], v[0:1], s[94:95] op_sel_hi:[1,0]
	v_pk_fma_f32 v[42:43], v[50:51], v[32:33], v[42:43] neg_lo:[0,0,1] neg_hi:[0,0,1]
	v_pk_mul_f32 v[32:33], v[80:81], v[32:33]
	v_cvt_pk_bf16_f32 v144, v0, v1
	v_pk_fma_f32 v[32:33], v[50:51], v[34:35], v[32:33]
	v_pk_mul_f32 v[34:35], v[52:53], v[28:29]
	v_pk_mul_f32 v[0:1], v[56:57], v[4:5] op_sel_hi:[0,1]
	v_pk_fma_f32 v[34:35], v[44:45], v[2:3], v[34:35] neg_lo:[0,0,1] neg_hi:[0,0,1]
	v_pk_mul_f32 v[2:3], v[52:53], v[2:3]
	s_waitcnt vmcnt(6)
	v_pk_mul_f32 v[0:1], v[82:83], v[0:1]
	v_pk_fma_f32 v[2:3], v[44:45], v[28:29], v[2:3]
	v_pk_mul_f32 v[28:29], v[56:57], v[150:151] op_sel_hi:[0,1]
	v_pk_mul_f32 v[2:3], v[2:3], s[94:95] op_sel_hi:[1,0]
	v_pk_mul_f32 v[28:29], v[30:31], v[28:29]
	v_pk_mul_f32 v[30:31], v[56:57], v[156:157] op_sel_hi:[0,1]
	v_cvt_pk_bf16_f32 v146, v2, v3
	v_pk_mul_f32 v[2:3], v[56:57], v[64:65] op_sel_hi:[0,1]
	v_pk_mul_f32 v[30:31], v[38:39], v[30:31]
	s_waitcnt vmcnt(4)
	v_pk_mul_f32 v[2:3], v[86:87], v[2:3]
	v_pk_mul_f32 v[36:37], v[54:55], v[30:31]
	s_waitcnt vmcnt(0)
	v_pk_mul_f32 v[4:5], v[94:95], v[2:3]
	v_pk_fma_f32 v[36:37], v[46:47], v[28:29], v[36:37] neg_lo:[0,0,1] neg_hi:[0,0,1]
	v_pk_mul_f32 v[28:29], v[54:55], v[28:29]
	v_pk_fma_f32 v[4:5], v[90:91], v[0:1], v[4:5] neg_lo:[0,0,1] neg_hi:[0,0,1]
	v_pk_mul_f32 v[0:1], v[94:95], v[0:1]
	v_pk_fma_f32 v[28:29], v[46:47], v[30:31], v[28:29]
	v_pk_fma_f32 v[0:1], v[90:91], v[2:3], v[0:1]
	v_pk_mul_f32 v[28:29], v[28:29], s[94:95] op_sel_hi:[1,0]
	v_pk_mul_f32 v[0:1], v[0:1], s[94:95] op_sel_hi:[1,0]
	v_cvt_pk_bf16_f32 v147, v28, v29
	v_pk_mul_f32 v[28:29], v[56:57], v[152:153] op_sel_hi:[0,1]
	v_cvt_pk_bf16_f32 v152, v0, v1
	v_and_b32_e32 v0, 0xffff0000, v112
	v_lshlrev_b32_e32 v1, 16, v112
	v_mul_f32_e32 v0, v0, v0
	v_fmac_f32_e32 v0, v1, v1
	v_lshlrev_b32_e32 v1, 16, v113
	v_fmac_f32_e32 v0, v1, v1
	v_and_b32_e32 v1, 0xffff0000, v113
	v_fmac_f32_e32 v0, v1, v1
	v_lshlrev_b32_e32 v1, 16, v114
	v_fmac_f32_e32 v0, v1, v1
	v_and_b32_e32 v1, 0xffff0000, v114
	v_fmac_f32_e32 v0, v1, v1
	v_lshlrev_b32_e32 v1, 16, v115
	v_fmac_f32_e32 v0, v1, v1
	v_and_b32_e32 v1, 0xffff0000, v115
	v_fmac_f32_e32 v0, v1, v1
	v_lshlrev_b32_e32 v1, 16, v116
	v_fmac_f32_e32 v0, v1, v1
	v_and_b32_e32 v1, 0xffff0000, v116
	v_fmac_f32_e32 v0, v1, v1
	v_lshlrev_b32_e32 v1, 16, v117
	v_fmac_f32_e32 v0, v1, v1
	v_and_b32_e32 v1, 0xffff0000, v117
	v_fmac_f32_e32 v0, v1, v1
	v_lshlrev_b32_e32 v1, 16, v118
	v_fmac_f32_e32 v0, v1, v1
	v_and_b32_e32 v1, 0xffff0000, v118
	v_fmac_f32_e32 v0, v1, v1
	v_lshlrev_b32_e32 v1, 16, v119
	v_fmac_f32_e32 v0, v1, v1
	v_and_b32_e32 v1, 0xffff0000, v119
	v_fmac_f32_e32 v0, v1, v1
	v_lshlrev_b32_e32 v1, 16, v120
	v_fmac_f32_e32 v0, v1, v1
	v_and_b32_e32 v1, 0xffff0000, v120
	v_fmac_f32_e32 v0, v1, v1
	v_lshlrev_b32_e32 v1, 16, v121
	v_fmac_f32_e32 v0, v1, v1
	v_and_b32_e32 v1, 0xffff0000, v121
	v_fmac_f32_e32 v0, v1, v1
	v_lshlrev_b32_e32 v1, 16, v122
	v_fmac_f32_e32 v0, v1, v1
	v_and_b32_e32 v1, 0xffff0000, v122
	v_fmac_f32_e32 v0, v1, v1
	v_lshlrev_b32_e32 v1, 16, v123
	v_fmac_f32_e32 v0, v1, v1
	v_and_b32_e32 v1, 0xffff0000, v123
	v_fmac_f32_e32 v0, v1, v1
	v_lshlrev_b32_e32 v1, 16, v124
	v_fmac_f32_e32 v0, v1, v1
	v_and_b32_e32 v1, 0xffff0000, v124
	v_fmac_f32_e32 v0, v1, v1
	v_lshlrev_b32_e32 v1, 16, v125
	v_fmac_f32_e32 v0, v1, v1
	v_and_b32_e32 v1, 0xffff0000, v125
	v_fmac_f32_e32 v0, v1, v1
	v_lshlrev_b32_e32 v1, 16, v126
	v_fmac_f32_e32 v0, v1, v1
	v_and_b32_e32 v1, 0xffff0000, v126
	v_fmac_f32_e32 v0, v1, v1
	v_lshlrev_b32_e32 v1, 16, v127
	v_fmac_f32_e32 v0, v1, v1
	v_and_b32_e32 v1, 0xffff0000, v127
	v_fmac_f32_e32 v0, v1, v1
	v_lshlrev_b32_e32 v1, 16, v128
	v_fmac_f32_e32 v0, v1, v1
	v_and_b32_e32 v1, 0xffff0000, v128
	v_fmac_f32_e32 v0, v1, v1
	v_lshlrev_b32_e32 v1, 16, v129
	v_fmac_f32_e32 v0, v1, v1
	v_and_b32_e32 v1, 0xffff0000, v129
	v_fmac_f32_e32 v0, v1, v1
	v_lshlrev_b32_e32 v1, 16, v130
	v_fmac_f32_e32 v0, v1, v1
	v_and_b32_e32 v1, 0xffff0000, v130
	v_fmac_f32_e32 v0, v1, v1
	v_lshlrev_b32_e32 v1, 16, v131
	v_fmac_f32_e32 v0, v1, v1
	v_and_b32_e32 v1, 0xffff0000, v131
	v_fmac_f32_e32 v0, v1, v1
	v_lshlrev_b32_e32 v1, 16, v132
	v_fmac_f32_e32 v0, v1, v1
	v_and_b32_e32 v1, 0xffff0000, v132
	v_fmac_f32_e32 v0, v1, v1
	v_lshlrev_b32_e32 v1, 16, v133
	v_fmac_f32_e32 v0, v1, v1
	v_and_b32_e32 v1, 0xffff0000, v133
	v_fmac_f32_e32 v0, v1, v1
	v_lshlrev_b32_e32 v1, 16, v134
	v_fmac_f32_e32 v0, v1, v1
	v_and_b32_e32 v1, 0xffff0000, v134
	v_fmac_f32_e32 v0, v1, v1
	v_lshlrev_b32_e32 v1, 16, v135
; __device__ __forceinline__ float bf2f(unsigned short v) { return __uint_as_float(((unsigned)v) << 16); }
; template <int DQK, bool MOBA>
; __device__ __forceinline__ void attn_unit(const Args& A, int b, int h, int qb, lptr lds) {
;     ...
;         float qss = 0.f;
; #pragma unroll
;         for (int s = 0; s < NS; ++s)
; #pragma unroll
;             for (int e = 0; e < 8; ++e) { const float f = bf2f((unsigned short)qf[s][e]); qss += f * f; }
;         qss += __shfl_xor(qss, 32);
;         float gmx = fmaxf(fabsf(A.gk_n[lane]), fabsf(A.gk_n[lane + 64]));
;         float grx = (DQK == 192) ? fabsf(A.gk_r[lane]) : 0.f;
;         float bmx = (MOBA && lane < 32) ? fabsf(A.relb[lane * 8 + h]) * 1.4426950408889634f : 0.f;
; #pragma unroll
;         for (int o_ = 1; o_ < 64; o_ <<= 1) { gmx = fmaxf(gmx, __shfl_xor(gmx, o_)); grx = fmaxf(grx, __shfl_xor(grx, o_)); bmx = fmaxf(bmx, __shfl_xor(bmx, o_)); }
	v_fmac_f32_e32 v0, v1, v1
	v_and_b32_e32 v1, 0xffff0000, v135
	v_fmac_f32_e32 v0, v1, v1
	v_lshlrev_b32_e32 v1, 16, v136
	v_fmac_f32_e32 v0, v1, v1
	v_and_b32_e32 v1, 0xffff0000, v136
	v_fmac_f32_e32 v0, v1, v1
	v_lshlrev_b32_e32 v1, 16, v137
	v_fmac_f32_e32 v0, v1, v1
	v_and_b32_e32 v1, 0xffff0000, v137
	v_pk_mul_f32 v[6:7], v[56:57], v[6:7] op_sel_hi:[0,1]
	v_fmac_f32_e32 v0, v1, v1
	v_lshlrev_b32_e32 v1, 16, v138
	v_pk_mul_f32 v[4:5], v[4:5], s[94:95] op_sel_hi:[1,0]
	v_pk_mul_f32 v[6:7], v[20:21], v[6:7]
	v_pk_mul_f32 v[20:21], v[56:57], v[66:67] op_sel_hi:[0,1]
	v_fmac_f32_e32 v0, v1, v1
	v_lshlrev_b32_e32 v1, 2, v110
	v_pk_mul_f32 v[16:17], v[16:17], v[20:21]
	v_cvt_pk_bf16_f32 v156, v4, v5
	global_load_dword v4, v1, s[38:39]
	global_load_dword v5, v1, s[38:39] offset:256
	v_pk_mul_f32 v[20:21], v[12:13], v[16:17]
	v_pk_mul_f32 v[2:3], v[56:57], v[104:105] op_sel_hi:[0,1]
	v_pk_fma_f32 v[20:21], v[8:9], v[6:7], v[20:21] neg_lo:[0,0,1] neg_hi:[0,0,1]
	v_pk_mul_f32 v[6:7], v[12:13], v[6:7]
	v_pk_mul_f32 v[28:29], v[88:89], v[28:29]
	v_pk_fma_f32 v[6:7], v[8:9], v[16:17], v[6:7]
	v_pk_mul_f32 v[2:3], v[84:85], v[2:3]
	v_pk_mul_f32 v[6:7], v[6:7], s[94:95] op_sel_hi:[1,0]
	v_pk_mul_f32 v[30:31], v[96:97], v[28:29]
	v_cvt_pk_bf16_f32 v154, v6, v7
	global_load_dword v6, v1, s[40:41]
	v_pk_fma_f32 v[30:31], v[92:93], v[2:3], v[30:31] neg_lo:[0,0,1] neg_hi:[0,0,1]
	v_pk_mul_f32 v[2:3], v[96:97], v[2:3]
	v_and_b32_e32 v1, 0xffff0000, v140
	v_pk_fma_f32 v[2:3], v[92:93], v[28:29], v[2:3]
	v_cvt_pk_bf16_f32 v143, v58, v59
	v_pk_mul_f32 v[2:3], v[2:3], s[94:95] op_sel_hi:[1,0]
	v_pk_mul_f32 v[40:41], v[40:41], s[94:95] op_sel_hi:[1,0]
	v_cvt_pk_bf16_f32 v153, v2, v3
	v_and_b32_e32 v2, 0xffff0000, v138
	v_fmac_f32_e32 v0, v2, v2
	v_lshlrev_b32_e32 v2, 16, v139
	v_fmac_f32_e32 v0, v2, v2
	v_and_b32_e32 v2, 0xffff0000, v139
	v_fmac_f32_e32 v0, v2, v2
	v_lshlrev_b32_e32 v2, 16, v140
	v_fmac_f32_e32 v0, v2, v2
	v_fmac_f32_e32 v0, v1, v1
	v_lshlrev_b32_e32 v1, 16, v141
	v_fmac_f32_e32 v0, v1, v1
	v_and_b32_e32 v1, 0xffff0000, v141
	v_fmac_f32_e32 v0, v1, v1
	v_lshlrev_b32_e32 v1, 16, v142
	v_fmac_f32_e32 v0, v1, v1
	v_and_b32_e32 v1, 0xffff0000, v142
	v_fmac_f32_e32 v0, v1, v1
	v_lshlrev_b32_e32 v1, 16, v143
	v_cvt_pk_bf16_f32 v148, v40, v41
	v_fmac_f32_e32 v0, v1, v1
	v_and_b32_e32 v1, 0xffff0000, v143
	v_pk_mul_f32 v[42:43], v[42:43], s[94:95] op_sel_hi:[1,0]
	v_fmac_f32_e32 v0, v1, v1
	v_lshlrev_b32_e32 v1, 16, v148
	v_cvt_pk_bf16_f32 v149, v42, v43
	v_fmac_f32_e32 v0, v1, v1
	v_and_b32_e32 v1, 0xffff0000, v148
	v_pk_mul_f32 v[34:35], v[34:35], s[94:95] op_sel_hi:[1,0]
	v_fmac_f32_e32 v0, v1, v1
	v_lshlrev_b32_e32 v1, 16, v149
	v_cvt_pk_bf16_f32 v150, v34, v35
	v_fmac_f32_e32 v0, v1, v1
	v_and_b32_e32 v1, 0xffff0000, v149
	v_pk_mul_f32 v[36:37], v[36:37], s[94:95] op_sel_hi:[1,0]
	v_fmac_f32_e32 v0, v1, v1
	v_lshlrev_b32_e32 v1, 16, v150
	v_cvt_pk_bf16_f32 v151, v36, v37
	v_fmac_f32_e32 v0, v1, v1
	v_and_b32_e32 v1, 0xffff0000, v150
	v_fmac_f32_e32 v0, v1, v1
	v_lshlrev_b32_e32 v1, 16, v151
	v_fmac_f32_e32 v0, v1, v1
	v_and_b32_e32 v1, 0xffff0000, v151
	v_pk_mul_f32 v[30:31], v[30:31], s[94:95] op_sel_hi:[1,0]
	v_pk_mul_f32 v[12:13], v[56:57], v[26:27] op_sel_hi:[0,1]
	v_fmac_f32_e32 v0, v1, v1
	v_lshlrev_b32_e32 v1, 16, v156
	v_pk_mul_f32 v[8:9], v[56:57], v[24:25] op_sel_hi:[0,1]
	v_pk_mul_f32 v[12:13], v[18:19], v[12:13]
	v_cvt_pk_bf16_f32 v157, v30, v31
	v_fmac_f32_e32 v0, v1, v1
	v_and_b32_e32 v1, 0xffff0000, v156
	v_pk_mul_f32 v[20:21], v[20:21], s[94:95] op_sel_hi:[1,0]
	v_pk_mul_f32 v[8:9], v[22:23], v[8:9]
	v_pk_mul_f32 v[16:17], v[14:15], v[12:13]
	v_fmac_f32_e32 v0, v1, v1
	v_lshlrev_b32_e32 v1, 16, v157
	v_pk_fma_f32 v[16:17], v[10:11], v[8:9], v[16:17] neg_lo:[0,0,1] neg_hi:[0,0,1]
	v_cvt_pk_bf16_f32 v158, v20, v21
	v_fmac_f32_e32 v0, v1, v1
	v_and_b32_e32 v1, 0xffff0000, v157
	v_pk_mul_f32 v[16:17], v[16:17], s[94:95] op_sel_hi:[1,0]
	v_fmac_f32_e32 v0, v1, v1
	v_lshlrev_b32_e32 v1, 16, v158
	v_cvt_pk_bf16_f32 v159, v16, v17
	v_fmac_f32_e32 v0, v1, v1
	v_and_b32_e32 v1, 0xffff0000, v158
	v_fmac_f32_e32 v0, v1, v1
	v_lshlrev_b32_e32 v1, 16, v159
	v_pk_mul_f32 v[32:33], v[32:33], s[94:95] op_sel_hi:[1,0]
	v_fmac_f32_e32 v0, v1, v1
	v_and_b32_e32 v1, 0xffff0000, v159
	v_cvt_pk_bf16_f32 v145, v32, v33
	v_fmac_f32_e32 v0, v1, v1
	v_lshlrev_b32_e32 v1, 16, v144
	v_fmac_f32_e32 v0, v1, v1
	v_and_b32_e32 v1, 0xffff0000, v144
	v_and_b32_e32 v3, 0xffff0000, v145
	v_lshlrev_b32_e32 v2, 16, v145
	v_fmac_f32_e32 v0, v1, v1
	v_pk_mul_f32 v[2:3], v[2:3], v[2:3]
	v_and_b32_e32 v1, 0xffff0000, v146
	v_add_f32_e32 v0, v2, v0
	v_add_f32_e32 v2, v3, v0
	v_lshlrev_b32_e32 v0, 16, v146
	v_pk_mul_f32 v[0:1], v[0:1], v[0:1]
	v_pk_mul_f32 v[8:9], v[14:15], v[8:9]
	v_add_f32_e32 v0, v0, v2
	v_add_f32_e32 v2, v1, v0
	v_lshlrev_b32_e32 v1, 16, v147
	v_and_b32_e32 v0, 0xffff0000, v147
	v_pk_mul_f32 v[0:1], v[0:1], v[0:1]
	v_pk_fma_f32 v[8:9], v[10:11], v[12:13], v[8:9]
	v_add_f32_e32 v1, v1, v2
	v_add_f32_e32 v2, v0, v1
	v_and_b32_e32 v1, 0xffff0000, v152
	v_lshlrev_b32_e32 v0, 16, v152
	v_pk_mul_f32 v[0:1], v[0:1], v[0:1]
	v_pk_mul_f32 v[8:9], v[8:9], s[94:95] op_sel_hi:[1,0]
	v_add_f32_e32 v0, v0, v2
	v_add_f32_e32 v2, v1, v0
	s_waitcnt vmcnt(1)
	v_max_f32_e64 v0, |v5|, |v5|
	v_max_f32_e64 v1, |v4|, |v4|
	v_max_f32_e32 v3, v1, v0
	v_xor_b32_e32 v0, 1, v206
	v_cmp_lt_i32_e32 vcc, v0, v109
	s_waitcnt vmcnt(0)
	v_and_b32_e32 v1, 0x7fffffff, v6
	v_cvt_pk_bf16_f32 v155, v8, v9
	v_cndmask_b32_e32 v0, v206, v0, vcc
	v_lshlrev_b32_e32 v0, 2, v0
	ds_bpermute_b32 v4, v0, v3
	ds_bpermute_b32 v5, v0, v1
	v_and_b32_e32 v1, 0xffff0000, v153
	v_lshlrev_b32_e32 v0, 16, v153
	v_pk_mul_f32 v[0:1], v[0:1], v[0:1]
	s_waitcnt lgkmcnt(1)
; template <int DQK, bool MOBA>
; __device__ __forceinline__ void attn_unit(const Args& A, int b, int h, int qb, lptr lds) {
;     ...
;         qss += __shfl_xor(qss, 32);
;         float gmx = fmaxf(fabsf(A.gk_n[lane]), fabsf(A.gk_n[lane + 64]));
;         float grx = (DQK == 192) ? fabsf(A.gk_r[lane]) : 0.f;
;         float bmx = (MOBA && lane < 32) ? fabsf(A.relb[lane * 8 + h]) * 1.4426950408889634f : 0.f;
; #pragma unroll
;         for (int o_ = 1; o_ < 64; o_ <<= 1) { gmx = fmaxf(gmx, __shfl_xor(gmx, o_)); grx = fmaxf(grx, __shfl_xor(grx, o_)); bmx = fmaxf(bmx, __shfl_xor(bmx, o_)); }
;         negm = -(sqrtf(qss * (128.0f * gmx * gmx + 64.0f * grx * grx)) * 1.01f + bmx + 0.01f);
	v_max_f32_e32 v4, v4, v4
	v_max_f32_e32 v3, v3, v4
	s_waitcnt lgkmcnt(0)
	v_max_f32_e32 v4, v5, v5
	v_max_f32_e64 v5, |v6|, |v6|
	v_xor_b32_e32 v6, 2, v206
	v_cmp_lt_i32_e32 vcc, v6, v109
	v_max_f32_e32 v4, v5, v4
	v_add_f32_e32 v0, v0, v2
	v_cndmask_b32_e32 v6, v206, v6, vcc
	v_lshlrev_b32_e32 v6, 2, v6
	ds_bpermute_b32 v7, v6, v3
	ds_bpermute_b32 v5, v6, v4
	v_and_b32_e32 v32, 15, v106
	v_lshlrev_b32_e32 v186, 4, v32
	v_add_u32_e32 v14, s4, v199
	s_waitcnt lgkmcnt(1)
	v_max_f32_e32 v2, v7, v7
	v_max_f32_e32 v2, v3, v2
	s_waitcnt lgkmcnt(0)
	v_max_f32_e32 v3, v5, v5
	v_xor_b32_e32 v5, 4, v206
	v_cmp_lt_i32_e32 vcc, v5, v109
	v_max_f32_e32 v3, v4, v3
	v_ashrrev_i32_e32 v15, 31, v14
	v_cndmask_b32_e32 v5, v206, v5, vcc
	v_lshlrev_b32_e32 v5, 2, v5
	ds_bpermute_b32 v6, v5, v2
	ds_bpermute_b32 v4, v5, v3
	v_add_f32_e32 v5, v1, v0
	v_and_b32_e32 v1, 0xffff0000, v154
	v_lshlrev_b64 v[14:15], 7, v[14:15]
	s_waitcnt lgkmcnt(1)
	v_max_f32_e32 v0, v6, v6
	v_max_f32_e32 v2, v2, v0
	s_waitcnt lgkmcnt(0)
	v_max_f32_e32 v0, v4, v4
	v_xor_b32_e32 v4, 8, v206
	v_cmp_lt_i32_e32 vcc, v4, v109
	v_max_f32_e32 v3, v3, v0
	v_lshlrev_b32_e32 v0, 16, v154
	v_cndmask_b32_e32 v4, v206, v4, vcc
	v_lshlrev_b32_e32 v4, 2, v4
	ds_bpermute_b32 v6, v4, v2
	ds_bpermute_b32 v4, v4, v3
	v_pk_mul_f32 v[0:1], v[0:1], v[0:1]
	v_lshlrev_b32_e32 v16, 4, v106
	v_add_f32_e32 v0, v0, v5
	s_waitcnt lgkmcnt(1)
	v_max_f32_e32 v6, v6, v6
	v_max_f32_e32 v2, v2, v6
	v_xor_b32_e32 v6, 16, v206
	v_cmp_lt_i32_e32 vcc, v6, v109
	s_waitcnt lgkmcnt(0)
	v_max_f32_e32 v4, v4, v4
	v_max_f32_e32 v3, v3, v4
	v_cndmask_b32_e32 v6, v206, v6, vcc
	v_lshlrev_b32_e32 v6, 2, v6
	ds_bpermute_b32 v7, v6, v2
	ds_bpermute_b32 v4, v6, v3
	v_add_f32_e32 v1, v1, v0
	v_and_b32_e32 v5, 0xffff0000, v155
	v_lshl_add_u64 v[14:15], s[86:87], 0, v[14:15]
	s_waitcnt lgkmcnt(1)
	v_max_f32_e32 v0, v7, v7
	v_max_f32_e32 v0, v2, v0
	s_waitcnt lgkmcnt(0)
	v_max_f32_e32 v2, v4, v4
	ds_bpermute_b32 v4, v196, v0
	v_max_f32_e32 v6, v3, v2
	ds_bpermute_b32 v7, v196, v6
	v_lshlrev_b32_e32 v3, 16, v155
	v_mov_b32_e32 v183, v3
	s_waitcnt lgkmcnt(1)
	v_max_f32_e32 v2, v4, v4
	v_max_f32_e32 v2, v0, v2
	s_waitcnt lgkmcnt(0)
	v_max_f32_e32 v0, v7, v7
	v_max_f32_e32 v4, v6, v0
	v_pk_mul_f32 v[8:9], v[2:3], v[182:183]
	v_mov_b32_e32 v0, v2
	v_pk_mul_f32 v[8:9], v[2:3], v[8:9]
	v_pk_fma_f32 v[0:1], v[2:3], v[182:183], v[0:1]
	v_mul_f32_e32 v6, 0x42800000, v4
	v_mov_b32_e32 v9, v1
	v_mov_b32_e32 v7, v5
	v_pk_fma_f32 v[26:27], v[4:5], v[6:7], v[8:9]
	ds_bpermute_b32 v30, v196, v27
	v_ashrrev_i32_e32 v0, 4, v106
	v_ashrrev_i32_e32 v1, 31, v0
	v_lshlrev_b64 v[2:3], 11, v[0:1]
	v_lshl_add_u64 v[4:5], s[0:1], 0, v[2:3]
	s_waitcnt lgkmcnt(0)
; template <int DQK, bool MOBA>
; __device__ __forceinline__ void attn_unit(const Args& A, int b, int h, int qb, lptr lds) {
;     ...
;         negm = -(sqrtf(qss * (128.0f * gmx * gmx + 64.0f * grx * grx)) * 1.01f + bmx + 0.01f);
;     }
;     const int NT = 4 * (own + 1);
;     u32x4 kr0, kr1, kr2, vr0, vr1; int pkr = 0;
;     kr2 = (u32x4){0u, 0u, 0u, 0u};
;     ...
;     f32x16 o[4];
; #pragma unroll
;     for (int d = 0; d < 4; ++d)
; #pragma unroll
;         for (int r = 0; r < 16; ++r) o[d][r] = 0.f;
;     float lrow = 0.f;
;     ATT_LOAD(0); ATT_WRITE(0);
;     if (NT > 1) ATT_LOAD(1);
;     __syncthreads();
	v_add_f32_e32 v27, v27, v30
	v_mul_f32_e32 v26, v26, v27
	v_mul_f32_e32 v27, 0x4f800000, v26
	v_cmp_gt_f32_e32 vcc, s35, v26
	v_lshl_add_u64 v[6:7], v[4:5], 0, v[186:187]
	v_add_u32_e32 v4, 32, v0
	v_cndmask_b32_e32 v26, v26, v27, vcc
	v_ashrrev_i32_e32 v5, 31, v4
	v_sqrt_f32_e32 v27, v26
	v_lshlrev_b64 v[28:29], 11, v[4:5]
	v_lshl_add_u64 v[8:9], s[0:1], 0, v[28:29]
	s_add_u32 s0, s92, s44
	s_addc_u32 s1, s93, s45
	s_add_u32 s0, s0, s6
	v_add_u32_e32 v30, -1, v27
	s_addc_u32 s1, s1, s7
	v_fma_f32 v31, -v30, v27, v26
	v_lshl_add_u64 v[18:19], s[0:1], 0, v[2:3]
	v_lshl_add_u64 v[22:23], s[0:1], 0, v[28:29]
	v_cmp_ge_f32_e64 s[0:1], 0, v31
	v_add_u32_e32 v31, 1, v27
	v_and_b32_e32 v188, 0x70, v16
	v_cndmask_b32_e64 v30, v27, v30, s[0:1]
	v_fma_f32 v27, -v31, v27, v26
	v_cmp_lt_f32_e64 s[0:1], 0, v27
	v_lshl_add_u64 v[10:11], v[8:9], 0, v[186:187]
	v_lshl_add_u64 v[14:15], v[14:15], 0, v[188:189]
	v_cndmask_b32_e64 v27, v30, v31, s[0:1]
	v_mul_f32_e32 v30, 0x37800000, v27
	v_cndmask_b32_e32 v27, v27, v30, vcc
	v_cmp_class_f32_e32 vcc, v26, v205
	s_mov_b32 s0, 0x3f8147ae
	global_load_dwordx4 v[6:9], v[6:7], off
	s_nop 0
	global_load_dwordx4 v[10:13], v[10:11], off
	v_cndmask_b32_e32 v26, v27, v26, vcc
	v_fma_f32 v26, v26, s0, 0
	v_add_f32_e32 v33, 0x3c23d70a, v26
	v_mov_b32_e32 v26, s15
	s_movk_i32 s0, 0xffe0
	v_bfi_b32 v197, s0, v26, v106
	s_or_b32 s0, s4, 64
	s_ashr_i32 s1, s0, 31
	s_lshl_b64 s[44:45], s[0:1], 11
	s_add_u32 s1, s92, s44
	s_addc_u32 s4, s93, s45
	s_add_u32 s46, s1, s6
	global_load_dwordx4 v[14:17], v[14:15], off
	v_lshl_add_u64 v[22:23], v[22:23], 0, v[186:187]
	s_addc_u32 s47, s4, s7
	global_load_dwordx4 v[22:25], v[22:23], off
	v_lshl_add_u64 v[26:27], s[46:47], 0, v[28:29]
	v_add_u32_e32 v30, s0, v199
	s_add_u32 s0, s90, s44
	v_lshl_add_u64 v[18:19], v[18:19], 0, v[186:187]
	v_lshl_add_u64 v[26:27], v[26:27], 0, v[186:187]
	v_ashrrev_i32_e32 v31, 31, v30
	s_addc_u32 s1, s91, s45
	global_load_dwordx4 v[18:21], v[18:19], off
	v_lshlrev_b64 v[30:31], 7, v[30:31]
	global_load_dwordx4 v[160:163], v[26:27], off
	v_lshl_add_u64 v[26:27], s[46:47], 0, v[2:3]
	s_add_u32 s0, s0, s6
	v_lshl_add_u64 v[26:27], v[26:27], 0, v[186:187]
	v_lshl_add_u64 v[30:31], s[86:87], 0, v[30:31]
	s_addc_u32 s1, s1, s7
	v_lshl_add_u64 v[30:31], v[30:31], 0, v[188:189]
	global_load_dwordx4 v[164:167], v[26:27], off
	global_load_dwordx4 v[172:175], v[30:31], off
	v_lshl_add_u64 v[26:27], s[0:1], 0, v[28:29]
	v_lshl_add_u64 v[26:27], v[26:27], 0, v[186:187]
	v_lshl_add_u64 v[2:3], s[0:1], 0, v[2:3]
	v_lshl_add_u64 v[2:3], v[2:3], 0, v[186:187]
	global_load_dwordx4 v[168:171], v[26:27], off
	global_load_dwordx4 v[176:179], v[2:3], off
	s_movk_i32 s0, 0x190
	v_mul_lo_u32 v200, v0, s0
	v_mul_lo_u32 v210, v199, s0
	s_movk_i32 s0, 0xffb0
	v_lshlrev_b64 v[26:27], 10, v[0:1]
	v_add3_u32 v1, 0, v200, v186
	v_add3_u32 v2, 0, v210, v188
	v_mul_lo_u32 v211, v0, s12
	v_mul_lo_u32 v0, v0, s0
	s_movk_i32 s0, 0x3200
	v_lshlrev_b32_e32 v183, 2, v107
	s_add_u32 s4, s90, s6
	v_lshlrev_b32_e32 v28, 3, v32
	v_lshlrev_b64 v[30:31], 10, v[4:5]
	s_addc_u32 s15, s91, s7
	v_xor_b32_e32 v64, 0x80000000, v33
	s_add_u32 s6, s92, s6
	v_mov_b32_e32 v3, v181
	v_mov_b32_e32 v4, v181
	v_mov_b32_e32 v5, v181
	v_lshlrev_b64 v[192:193], 1, v[26:27]
	v_lshlrev_b64 v[194:195], 1, v[30:31]
	v_add_u32_e32 v201, 0x3200, v200
	v_add_u32_e32 v212, 0x2800, v211
	v_mov_b32_e32 v65, v64
	v_mov_b32_e32 v66, v64
	v_mov_b32_e32 v67, v64
	v_mov_b32_e32 v68, v64
	v_mov_b32_e32 v69, v64
	v_mov_b32_e32 v70, v64
	v_mov_b32_e32 v71, v64
	v_mov_b32_e32 v72, v64
	v_mov_b32_e32 v73, v64
	v_mov_b32_e32 v74, v64
	v_mov_b32_e32 v75, v64
	v_mov_b32_e32 v76, v64
	v_mov_b32_e32 v77, v64
	v_mov_b32_e32 v78, v64
	v_mov_b32_e32 v79, v64
	v_lshl_add_u64 v[190:191], s[86:87], 0, v[188:189]
	s_waitcnt vmcnt(9)
	ds_write_b128 v1, v[6:9]
	s_waitcnt vmcnt(8)
	ds_write_b128 v1, v[10:13] offset:12800
	v_mov_b32_e32 v6, v181
	v_mov_b32_e32 v7, v181
	v_mov_b32_e32 v8, v181
	v_mov_b32_e32 v9, v181
	v_mov_b32_e32 v10, v181
	v_mov_b32_e32 v11, v181
	v_mov_b32_e32 v12, v181
	v_mov_b32_e32 v13, v181
	s_addc_u32 s7, s93, s7
	s_or_b32 s13, s13, 0xc0
	v_mov_b32_e32 v187, 0
	s_waitcnt vmcnt(7)
	ds_write_b128 v2, v[14:17] offset:256
	v_add_u32_e32 v2, v1, v0
	v_add3_u32 v0, v1, s0, v0
	s_waitcnt vmcnt(6)
	ds_write_b128 v0, v[22:25] offset:48640
	v_mul_u32_u24_e32 v0, 0x190, v108
	v_add3_u32 v213, 0, v0, v180
	v_lshrrev_b32_e32 v0, 2, v106
	v_and_or_b32 v0, v0, 3, v183
	v_lshlrev_b32_e32 v1, 1, v106
	v_mad_u32_u24 v0, v0, s12, 0
	v_and_b32_e32 v1, 32, v1
	s_waitcnt vmcnt(5)
	ds_write_b128 v2, v[18:21] offset:51200
	v_lshlrev_b32_e32 v2, 3, v106
	v_and_b32_e32 v2, 24, v2
	v_mov_b32_e32 v14, v181
	v_mov_b32_e32 v15, v181
	v_add3_u32 v198, v0, v1, v2
	v_mov_b32_e32 v0, v181
	v_mov_b32_e32 v1, v181
	v_mov_b32_e32 v2, v181
	v_lshlrev_b32_e32 v180, 1, v28
	v_mov_b64_e32 v[30:31], v[14:15]
	v_mov_b64_e32 v[46:47], v[14:15]
	v_mov_b64_e32 v[62:63], v[14:15]
	v_mov_b64_e32 v[28:29], v[12:13]
	v_mov_b64_e32 v[26:27], v[10:11]
	v_mov_b64_e32 v[24:25], v[8:9]
	v_mov_b64_e32 v[22:23], v[6:7]
	v_mov_b64_e32 v[20:21], v[4:5]
	v_mov_b64_e32 v[18:19], v[2:3]
	v_mov_b64_e32 v[16:17], v[0:1]
	v_mov_b64_e32 v[44:45], v[12:13]
	v_mov_b64_e32 v[42:43], v[10:11]
	v_mov_b64_e32 v[40:41], v[8:9]
	v_mov_b64_e32 v[38:39], v[6:7]
	v_mov_b64_e32 v[36:37], v[4:5]
	v_mov_b64_e32 v[34:35], v[2:3]
	v_mov_b64_e32 v[32:33], v[0:1]
	v_mov_b64_e32 v[60:61], v[12:13]
	v_mov_b64_e32 v[58:59], v[10:11]
	v_mov_b64_e32 v[56:57], v[8:9]
	v_mov_b64_e32 v[54:55], v[6:7]
	v_mov_b64_e32 v[52:53], v[4:5]
	v_mov_b64_e32 v[50:51], v[2:3]
	v_mov_b64_e32 v[48:49], v[0:1]
	s_waitcnt lgkmcnt(0)
	s_barrier
	s_branch .LBB0_812
